# packed f32 VALU (v_pk_mul/v_pk_add) replaced by scalar pairs in the retention, stick-breaking and cross-attention loops (bit-identical arithmetic; packed ops cost more beside MFMAs with two waves per
# speedup vs baseline: 1.0066x; 1.0066x over previous
.LBB0_431:
	v_add_u32_e32 v0, s18, v231
	v_add3_u32 v0, v0, v241, v248
	v_mul_f32_e32 v92, v222, v92
	v_mul_f32_e32 v93, v223, v93
	v_mul_f32_e32 v90, v220, v90
	v_mul_f32_e32 v91, v221, v91
	v_mul_f32_e32 v88, v218, v88
	v_mul_f32_e32 v89, v219, v89
	v_mul_f32_e32 v86, v212, v86
	v_mul_f32_e32 v87, v213, v87
	v_mul_f32_e32 v84, v210, v84
	v_mul_f32_e32 v85, v211, v85
	v_mul_f32_e32 v82, v206, v82
	v_mul_f32_e32 v83, v207, v83
	v_mul_f32_e32 v194, v216, v80
	v_mul_f32_e32 v195, v217, v81
	v_mul_f32_e32 v206, v214, v78
	v_mul_f32_e32 v207, v215, v79
	v_mul_f32_e32 v208, v208, v76
	v_mul_f32_e32 v209, v209, v77
	v_mul_f32_e32 v204, v204, v74
	v_mul_f32_e32 v205, v205, v75
	v_mul_f32_e32 v78, v202, v72
	v_mul_f32_e32 v79, v203, v73
	v_mul_f32_e32 v76, v192, v70
	v_mul_f32_e32 v77, v193, v71
	v_mul_f32_e32 v80, v190, v68
	v_mul_f32_e32 v81, v191, v69
	v_mul_f32_e32 v74, v188, v66
	v_mul_f32_e32 v75, v189, v67
	v_add_u32_e32 v188, v0, v249
	v_add_u32_e32 v190, v0, v246
	v_cvt_pk_bf16_f32 v66, v82, v83
	v_cvt_pk_bf16_f32 v67, v84, v85
	v_cvt_pk_bf16_f32 v68, v86, v87
	v_cvt_pk_bf16_f32 v69, v88, v89
	v_cvt_pk_bf16_f32 v70, v90, v91
	v_cvt_pk_bf16_f32 v71, v92, v93
	v_cvt_pk_bf16_f32 v74, v74, v75
	v_cvt_pk_bf16_f32 v75, v80, v81
	v_cvt_pk_bf16_f32 v76, v76, v77
	v_cvt_pk_bf16_f32 v77, v78, v79
	v_add_u32_e32 v189, v0, v247
	ds_read_b64_tr_b16 v[78:79], v188 offset:16384
	ds_read_b64_tr_b16 v[80:81], v188 offset:18432
	ds_read_b64_tr_b16 v[82:83], v189 offset:16384
	ds_read_b64_tr_b16 v[84:85], v189 offset:18432
	v_add_u32_e32 v0, v0, v245
	ds_read_b64_tr_b16 v[86:87], v190 offset:16384
	ds_read_b64_tr_b16 v[88:89], v190 offset:18432
	ds_read_b64_tr_b16 v[90:91], v0 offset:16384
	ds_read_b64_tr_b16 v[92:93], v0 offset:18432
	v_mul_f32_e32 v96, v226, v96
	v_mul_f32_e32 v97, v227, v97
	v_mul_f32_e32 v94, v224, v94
	v_mul_f32_e32 v95, v225, v95
	v_cvt_pk_bf16_f32 v73, v96, v97
	v_cvt_pk_bf16_f32 v72, v94, v95
	v_cvt_pk_bf16_f32 v94, v204, v205
	v_cvt_pk_bf16_f32 v95, v208, v209
	v_cvt_pk_bf16_f32 v96, v206, v207
	v_cvt_pk_bf16_f32 v97, v194, v195
	s_waitcnt lgkmcnt(6)
	v_mfma_f32_32x32x16_bf16 v[50:65], v[78:81], v[66:69], v[50:65]
	s_waitcnt lgkmcnt(4)
	v_mfma_f32_32x32x16_bf16 v[34:49], v[82:85], v[66:69], v[34:49]
	s_waitcnt lgkmcnt(2)
	v_mfma_f32_32x32x16_bf16 v[18:33], v[86:89], v[66:69], v[18:33]
	s_waitcnt lgkmcnt(0)
	v_mfma_f32_32x32x16_bf16 v[2:17], v[90:93], v[66:69], v[2:17]
	ds_read_b64_tr_b16 v[66:67], v188 offset:20480
	ds_read_b64_tr_b16 v[68:69], v188 offset:22528
	ds_read_b64_tr_b16 v[78:79], v189 offset:20480
	ds_read_b64_tr_b16 v[80:81], v189 offset:22528
	ds_read_b64_tr_b16 v[82:83], v190 offset:20480
	ds_read_b64_tr_b16 v[84:85], v190 offset:22528
	ds_read_b64_tr_b16 v[86:87], v0 offset:20480
	ds_read_b64_tr_b16 v[88:89], v0 offset:22528
	s_waitcnt lgkmcnt(6)
	v_mfma_f32_32x32x16_bf16 v[50:65], v[66:69], v[70:73], v[50:65]
	s_waitcnt lgkmcnt(4)
	v_mfma_f32_32x32x16_bf16 v[34:49], v[78:81], v[70:73], v[34:49]
	s_waitcnt lgkmcnt(2)
	v_mfma_f32_32x32x16_bf16 v[18:33], v[82:85], v[70:73], v[18:33]
	s_waitcnt lgkmcnt(0)
	v_mfma_f32_32x32x16_bf16 v[2:17], v[86:89], v[70:73], v[2:17]
	ds_read_b64_tr_b16 v[66:67], v188 offset:24576
	ds_read_b64_tr_b16 v[68:69], v188 offset:26624
	ds_read_b64_tr_b16 v[70:71], v189 offset:24576
	ds_read_b64_tr_b16 v[72:73], v189 offset:26624
	ds_read_b64_tr_b16 v[78:79], v190 offset:24576
	ds_read_b64_tr_b16 v[80:81], v190 offset:26624
	ds_read_b64_tr_b16 v[82:83], v0 offset:24576
	ds_read_b64_tr_b16 v[84:85], v0 offset:26624
	s_waitcnt lgkmcnt(6)
	v_mfma_f32_32x32x16_bf16 v[50:65], v[66:69], v[74:77], v[50:65]
	s_waitcnt lgkmcnt(4)
	v_mfma_f32_32x32x16_bf16 v[34:49], v[70:73], v[74:77], v[34:49]
	s_waitcnt lgkmcnt(2)
	v_mfma_f32_32x32x16_bf16 v[18:33], v[78:81], v[74:77], v[18:33]
	s_waitcnt lgkmcnt(0)
	v_mfma_f32_32x32x16_bf16 v[2:17], v[82:85], v[74:77], v[2:17]
	ds_read_b64_tr_b16 v[66:67], v188 offset:28672
	ds_read_b64_tr_b16 v[68:69], v188 offset:30720
	ds_read_b64_tr_b16 v[70:71], v189 offset:28672
	ds_read_b64_tr_b16 v[72:73], v189 offset:30720
	ds_read_b64_tr_b16 v[74:75], v190 offset:28672
	ds_read_b64_tr_b16 v[76:77], v190 offset:30720
	ds_read_b64_tr_b16 v[78:79], v0 offset:28672
	ds_read_b64_tr_b16 v[80:81], v0 offset:30720
	s_waitcnt lgkmcnt(6)
	v_mfma_f32_32x32x16_bf16 v[50:65], v[66:69], v[94:97], v[50:65]
	s_waitcnt lgkmcnt(4)
	v_mfma_f32_32x32x16_bf16 v[34:49], v[70:73], v[94:97], v[34:49]
	s_waitcnt lgkmcnt(2)
	v_mfma_f32_32x32x16_bf16 v[18:33], v[74:77], v[94:97], v[18:33]
	s_waitcnt lgkmcnt(0)
	v_mfma_f32_32x32x16_bf16 v[2:17], v[78:81], v[94:97], v[2:17]

.LBB0_437:
	v_add_u32_e32 v0, s19, v231
	v_add3_u32 v0, v0, v241, v248
	v_mul_f32_e32 v92, v214, v92
	v_mul_f32_e32 v93, v215, v93
	v_mul_f32_e32 v90, v212, v90
	v_mul_f32_e32 v91, v213, v91
	v_mul_f32_e32 v88, v210, v88
	v_mul_f32_e32 v89, v211, v89
	v_mul_f32_e32 v86, v204, v86
	v_mul_f32_e32 v87, v205, v87
	v_mul_f32_e32 v84, v202, v84
	v_mul_f32_e32 v85, v203, v85
	v_mul_f32_e32 v82, v190, v82
	v_mul_f32_e32 v83, v191, v83
	v_mul_f32_e32 v190, v208, v80
	v_mul_f32_e32 v191, v209, v81
	v_mul_f32_e32 v194, v206, v78
	v_mul_f32_e32 v195, v207, v79
	v_mul_f32_e32 v192, v192, v76
	v_mul_f32_e32 v193, v193, v77
	v_mul_f32_e32 v188, v188, v74
	v_mul_f32_e32 v189, v189, v75
	v_mul_f32_e32 v78, v186, v72
	v_mul_f32_e32 v79, v187, v73
	v_mul_f32_e32 v76, v184, v70
	v_mul_f32_e32 v77, v185, v71
	v_mul_f32_e32 v80, v182, v68
	v_mul_f32_e32 v81, v183, v69
	v_mul_f32_e32 v74, v180, v66
	v_mul_f32_e32 v75, v181, v67
	v_add_u32_e32 v180, v0, v249
	v_add_u32_e32 v182, v0, v246
	v_cvt_pk_bf16_f32 v66, v82, v83
	v_cvt_pk_bf16_f32 v67, v84, v85
	v_cvt_pk_bf16_f32 v68, v86, v87
	v_cvt_pk_bf16_f32 v69, v88, v89
	v_cvt_pk_bf16_f32 v70, v90, v91
	v_cvt_pk_bf16_f32 v71, v92, v93
	v_cvt_pk_bf16_f32 v74, v74, v75
	v_cvt_pk_bf16_f32 v75, v80, v81
	v_cvt_pk_bf16_f32 v76, v76, v77
	v_cvt_pk_bf16_f32 v77, v78, v79
	v_add_u32_e32 v181, v0, v247
	ds_read_b64_tr_b16 v[78:79], v180 offset:16384
	ds_read_b64_tr_b16 v[80:81], v180 offset:18432
	ds_read_b64_tr_b16 v[82:83], v181 offset:16384
	ds_read_b64_tr_b16 v[84:85], v181 offset:18432
	v_add_u32_e32 v0, v0, v245
	ds_read_b64_tr_b16 v[86:87], v182 offset:16384
	ds_read_b64_tr_b16 v[88:89], v182 offset:18432
	ds_read_b64_tr_b16 v[90:91], v0 offset:16384
	ds_read_b64_tr_b16 v[92:93], v0 offset:18432
	v_mul_f32_e32 v96, v218, v96
	v_mul_f32_e32 v97, v219, v97
	v_mul_f32_e32 v94, v216, v94
	v_mul_f32_e32 v95, v217, v95
	v_cvt_pk_bf16_f32 v73, v96, v97
	v_cvt_pk_bf16_f32 v72, v94, v95
	v_cvt_pk_bf16_f32 v94, v188, v189
	v_cvt_pk_bf16_f32 v95, v192, v193
	v_cvt_pk_bf16_f32 v96, v194, v195
	v_cvt_pk_bf16_f32 v97, v190, v191
	s_waitcnt lgkmcnt(6)
	v_mfma_f32_32x32x16_bf16 v[50:65], v[78:81], v[66:69], v[50:65]
	s_waitcnt lgkmcnt(4)
	v_mfma_f32_32x32x16_bf16 v[34:49], v[82:85], v[66:69], v[34:49]
	s_waitcnt lgkmcnt(2)
	v_mfma_f32_32x32x16_bf16 v[18:33], v[86:89], v[66:69], v[18:33]
	s_waitcnt lgkmcnt(0)
	v_mfma_f32_32x32x16_bf16 v[2:17], v[90:93], v[66:69], v[2:17]
	ds_read_b64_tr_b16 v[66:67], v180 offset:20480
	ds_read_b64_tr_b16 v[68:69], v180 offset:22528
	ds_read_b64_tr_b16 v[78:79], v181 offset:20480
	ds_read_b64_tr_b16 v[80:81], v181 offset:22528
	ds_read_b64_tr_b16 v[82:83], v182 offset:20480
	ds_read_b64_tr_b16 v[84:85], v182 offset:22528
	ds_read_b64_tr_b16 v[86:87], v0 offset:20480
	ds_read_b64_tr_b16 v[88:89], v0 offset:22528
	s_waitcnt lgkmcnt(6)
	v_mfma_f32_32x32x16_bf16 v[50:65], v[66:69], v[70:73], v[50:65]
	s_waitcnt lgkmcnt(4)
	v_mfma_f32_32x32x16_bf16 v[34:49], v[78:81], v[70:73], v[34:49]
	s_waitcnt lgkmcnt(2)
	v_mfma_f32_32x32x16_bf16 v[18:33], v[82:85], v[70:73], v[18:33]
	s_waitcnt lgkmcnt(0)
	v_mfma_f32_32x32x16_bf16 v[2:17], v[86:89], v[70:73], v[2:17]
	ds_read_b64_tr_b16 v[66:67], v180 offset:24576
	ds_read_b64_tr_b16 v[68:69], v180 offset:26624
	ds_read_b64_tr_b16 v[70:71], v181 offset:24576
	ds_read_b64_tr_b16 v[72:73], v181 offset:26624
	ds_read_b64_tr_b16 v[78:79], v182 offset:24576
	ds_read_b64_tr_b16 v[80:81], v182 offset:26624
	ds_read_b64_tr_b16 v[82:83], v0 offset:24576
	ds_read_b64_tr_b16 v[84:85], v0 offset:26624
	s_waitcnt lgkmcnt(6)
	v_mfma_f32_32x32x16_bf16 v[50:65], v[66:69], v[74:77], v[50:65]
	s_waitcnt lgkmcnt(4)
	v_mfma_f32_32x32x16_bf16 v[34:49], v[70:73], v[74:77], v[34:49]
	s_waitcnt lgkmcnt(2)
	v_mfma_f32_32x32x16_bf16 v[18:33], v[78:81], v[74:77], v[18:33]
	s_waitcnt lgkmcnt(0)
	v_mfma_f32_32x32x16_bf16 v[2:17], v[82:85], v[74:77], v[2:17]
	ds_read_b64_tr_b16 v[66:67], v180 offset:28672
	ds_read_b64_tr_b16 v[68:69], v180 offset:30720
	ds_read_b64_tr_b16 v[70:71], v181 offset:28672
	ds_read_b64_tr_b16 v[72:73], v181 offset:30720
	ds_read_b64_tr_b16 v[74:75], v182 offset:28672
	ds_read_b64_tr_b16 v[76:77], v182 offset:30720
	ds_read_b64_tr_b16 v[78:79], v0 offset:28672
	ds_read_b64_tr_b16 v[80:81], v0 offset:30720
	s_waitcnt lgkmcnt(6)
	v_mfma_f32_32x32x16_bf16 v[50:65], v[66:69], v[94:97], v[50:65]
	s_waitcnt lgkmcnt(4)
	v_mfma_f32_32x32x16_bf16 v[34:49], v[70:73], v[94:97], v[34:49]
	s_waitcnt lgkmcnt(2)
	v_mfma_f32_32x32x16_bf16 v[18:33], v[74:77], v[94:97], v[18:33]
	s_waitcnt lgkmcnt(0)
	v_mfma_f32_32x32x16_bf16 v[2:17], v[78:81], v[94:97], v[2:17]

.LBB0_443:
	v_add_u32_e32 v0, s19, v231
	v_add3_u32 v0, v0, v241, v248
	v_mul_f32_e32 v92, v190, v92
	v_mul_f32_e32 v93, v191, v93
	v_mul_f32_e32 v90, v188, v90
	v_mul_f32_e32 v91, v189, v91
	v_mul_f32_e32 v88, v186, v88
	v_mul_f32_e32 v89, v187, v89
	v_mul_f32_e32 v86, v180, v86
	v_mul_f32_e32 v87, v181, v87
	v_mul_f32_e32 v84, v178, v84
	v_mul_f32_e32 v85, v179, v85
	v_mul_f32_e32 v82, v174, v82
	v_mul_f32_e32 v83, v175, v83
	v_mul_f32_e32 v174, v184, v80
	v_mul_f32_e32 v175, v185, v81
	v_mul_f32_e32 v178, v182, v78
	v_mul_f32_e32 v179, v183, v79
	v_mul_f32_e32 v176, v176, v76
	v_mul_f32_e32 v177, v177, v77
	v_mul_f32_e32 v172, v172, v74
	v_mul_f32_e32 v173, v173, v75
	v_mul_f32_e32 v78, v170, v72
	v_mul_f32_e32 v79, v171, v73
	v_mul_f32_e32 v76, v168, v70
	v_mul_f32_e32 v77, v169, v71
	v_mul_f32_e32 v80, v166, v68
	v_mul_f32_e32 v81, v167, v69
	v_mul_f32_e32 v74, v164, v66
	v_mul_f32_e32 v75, v165, v67
	v_add_u32_e32 v164, v0, v249
	v_add_u32_e32 v166, v0, v246
	v_cvt_pk_bf16_f32 v66, v82, v83
	v_cvt_pk_bf16_f32 v67, v84, v85
	v_cvt_pk_bf16_f32 v68, v86, v87
	v_cvt_pk_bf16_f32 v69, v88, v89
	v_cvt_pk_bf16_f32 v70, v90, v91
	v_cvt_pk_bf16_f32 v71, v92, v93
	v_cvt_pk_bf16_f32 v74, v74, v75
	v_cvt_pk_bf16_f32 v75, v80, v81
	v_cvt_pk_bf16_f32 v76, v76, v77
	v_cvt_pk_bf16_f32 v77, v78, v79
	v_add_u32_e32 v165, v0, v247
	ds_read_b64_tr_b16 v[78:79], v164 offset:16384
	ds_read_b64_tr_b16 v[80:81], v164 offset:18432
	ds_read_b64_tr_b16 v[82:83], v165 offset:16384
	ds_read_b64_tr_b16 v[84:85], v165 offset:18432
	v_add_u32_e32 v0, v0, v245
	ds_read_b64_tr_b16 v[86:87], v166 offset:16384
	ds_read_b64_tr_b16 v[88:89], v166 offset:18432
	ds_read_b64_tr_b16 v[90:91], v0 offset:16384
	ds_read_b64_tr_b16 v[92:93], v0 offset:18432
	v_mul_f32_e32 v96, v202, v96
	v_mul_f32_e32 v97, v203, v97
	v_mul_f32_e32 v94, v192, v94
	v_mul_f32_e32 v95, v193, v95
	v_cvt_pk_bf16_f32 v73, v96, v97
	v_cvt_pk_bf16_f32 v72, v94, v95
	v_cvt_pk_bf16_f32 v94, v172, v173
	v_cvt_pk_bf16_f32 v95, v176, v177
	v_cvt_pk_bf16_f32 v96, v178, v179
	v_cvt_pk_bf16_f32 v97, v174, v175
	s_waitcnt lgkmcnt(6)
	v_mfma_f32_32x32x16_bf16 v[50:65], v[78:81], v[66:69], v[50:65]
	s_waitcnt lgkmcnt(4)
	v_mfma_f32_32x32x16_bf16 v[34:49], v[82:85], v[66:69], v[34:49]
	s_waitcnt lgkmcnt(2)
	v_mfma_f32_32x32x16_bf16 v[18:33], v[86:89], v[66:69], v[18:33]
	s_waitcnt lgkmcnt(0)
	v_mfma_f32_32x32x16_bf16 v[2:17], v[90:93], v[66:69], v[2:17]
	ds_read_b64_tr_b16 v[66:67], v164 offset:20480
	ds_read_b64_tr_b16 v[68:69], v164 offset:22528
	ds_read_b64_tr_b16 v[78:79], v165 offset:20480
	ds_read_b64_tr_b16 v[80:81], v165 offset:22528
	ds_read_b64_tr_b16 v[82:83], v166 offset:20480
	ds_read_b64_tr_b16 v[84:85], v166 offset:22528
	ds_read_b64_tr_b16 v[86:87], v0 offset:20480
	ds_read_b64_tr_b16 v[88:89], v0 offset:22528
	s_waitcnt lgkmcnt(6)
	v_mfma_f32_32x32x16_bf16 v[50:65], v[66:69], v[70:73], v[50:65]
	s_waitcnt lgkmcnt(4)
	v_mfma_f32_32x32x16_bf16 v[34:49], v[78:81], v[70:73], v[34:49]
	s_waitcnt lgkmcnt(2)
	v_mfma_f32_32x32x16_bf16 v[18:33], v[82:85], v[70:73], v[18:33]
	s_waitcnt lgkmcnt(0)
	v_mfma_f32_32x32x16_bf16 v[2:17], v[86:89], v[70:73], v[2:17]
	ds_read_b64_tr_b16 v[66:67], v164 offset:24576
	ds_read_b64_tr_b16 v[68:69], v164 offset:26624
	ds_read_b64_tr_b16 v[70:71], v165 offset:24576
	ds_read_b64_tr_b16 v[72:73], v165 offset:26624
	ds_read_b64_tr_b16 v[78:79], v166 offset:24576
	ds_read_b64_tr_b16 v[80:81], v166 offset:26624
	ds_read_b64_tr_b16 v[82:83], v0 offset:24576
	ds_read_b64_tr_b16 v[84:85], v0 offset:26624
	s_waitcnt lgkmcnt(6)
	v_mfma_f32_32x32x16_bf16 v[50:65], v[66:69], v[74:77], v[50:65]
	s_waitcnt lgkmcnt(4)
	v_mfma_f32_32x32x16_bf16 v[34:49], v[70:73], v[74:77], v[34:49]
	s_waitcnt lgkmcnt(2)
	v_mfma_f32_32x32x16_bf16 v[18:33], v[78:81], v[74:77], v[18:33]
	s_waitcnt lgkmcnt(0)
	v_mfma_f32_32x32x16_bf16 v[2:17], v[82:85], v[74:77], v[2:17]
	ds_read_b64_tr_b16 v[66:67], v164 offset:28672
	ds_read_b64_tr_b16 v[68:69], v164 offset:30720
	ds_read_b64_tr_b16 v[70:71], v165 offset:28672
	ds_read_b64_tr_b16 v[72:73], v165 offset:30720
	ds_read_b64_tr_b16 v[74:75], v166 offset:28672
	ds_read_b64_tr_b16 v[76:77], v166 offset:30720
	ds_read_b64_tr_b16 v[78:79], v0 offset:28672
	ds_read_b64_tr_b16 v[80:81], v0 offset:30720
	s_waitcnt lgkmcnt(6)
	v_mfma_f32_32x32x16_bf16 v[50:65], v[66:69], v[94:97], v[50:65]
	s_waitcnt lgkmcnt(4)
	v_mfma_f32_32x32x16_bf16 v[34:49], v[70:73], v[94:97], v[34:49]
	s_waitcnt lgkmcnt(2)
	v_mfma_f32_32x32x16_bf16 v[18:33], v[74:77], v[94:97], v[18:33]
	s_waitcnt lgkmcnt(0)
	v_mfma_f32_32x32x16_bf16 v[2:17], v[78:81], v[94:97], v[2:17]

.LBB0_461:
	s_add_i32 s12, s73, s15
	v_add_u32_e32 v38, s12, v98
	v_add_u32_e32 v34, v38, v101
	ds_read_b128 v[34:37], v34
	v_add_u32_e32 v39, v38, v102
	ds_read_b128 v[86:89], v39
	v_add_u32_e32 v39, v38, v103
	v_add_u32_e32 v38, v38, v104
	ds_read_b128 v[114:117], v38
	v_add3_u32 v38, s12, v99, v100
	ds_read_b128 v[110:113], v39
	v_add3_u32 v39, v38, v106, v105
	v_add3_u32 v38, v38, v107, v105
	ds_read_b64_tr_b16 v[78:79], v39 offset:4096
	ds_read_b64_tr_b16 v[80:81], v39 offset:5120
	ds_read_b64_tr_b16 v[70:71], v39 offset:6144
	ds_read_b64_tr_b16 v[72:73], v39 offset:7168
	ds_read_b64_tr_b16 v[74:75], v38 offset:4096
	ds_read_b64_tr_b16 v[76:77], v38 offset:5120
	ds_read_b64_tr_b16 v[66:67], v38 offset:6144
	ds_read_b64_tr_b16 v[68:69], v38 offset:7168
	s_waitcnt lgkmcnt(11)
	v_mfma_f32_32x32x16_bf16 v[34:49], v[34:37], v[50:53], 0
	s_or_b32 s15, s14, 31
	s_mov_b64 s[12:13], -1
	s_cmp_ge_i32 s15, s85
	s_waitcnt lgkmcnt(10)
	v_mfma_f32_32x32x16_bf16 v[34:49], v[86:89], v[54:57], v[34:49]
	s_waitcnt lgkmcnt(8)
	v_mfma_f32_32x32x16_bf16 v[34:49], v[110:113], v[58:61], v[34:49]
	v_mfma_f32_32x32x16_bf16 v[34:49], v[114:117], v[62:65], v[34:49]
	s_nop 11
	v_min_f32_e32 v117, 0x42a00000, v34
	v_min_f32_e32 v116, 0x42a00000, v35
	v_min_f32_e32 v115, 0x42a00000, v36
	v_min_f32_e32 v114, 0x42a00000, v37
	v_min_f32_e32 v89, 0x42a00000, v38
	v_min_f32_e32 v88, 0x42a00000, v39
	v_min_f32_e32 v86, 0x42a00000, v40
	v_min_f32_e32 v87, 0x42a00000, v41
	v_min_f32_e32 v90, 0x42a00000, v42
	v_min_f32_e32 v91, 0x42a00000, v43
	v_min_f32_e32 v113, 0x42a00000, v44
	v_min_f32_e32 v112, 0x42a00000, v45
	v_min_f32_e32 v111, 0x42a00000, v46
	v_min_f32_e32 v110, 0x42a00000, v47
	v_min_f32_e32 v109, 0x42a00000, v48
	v_min_f32_e32 v85, 0x42a00000, v49
	s_cbranch_scc0 .LBB0_463
	v_or_b32_e32 v35, s14, v97
	v_or_b32_e32 v37, 1, v35
	v_cmp_lt_i32_e64 s[12:13], v37, v82
	v_exp_f32_e32 v120, v115
	v_or_b32_e32 v38, 2, v35
	v_cmp_lt_i32_e64 s[14:15], v38, v82
	v_or_b32_e32 v39, 3, v35
	v_add_f32_e32 v37, 1.0, v120
	v_rcp_f32_e32 v37, v37
	v_cmp_lt_i32_e64 s[16:17], v39, v82
	v_or_b32_e32 v39, 8, v35
	v_cmp_lt_i32_e64 s[18:19], v39, v82
	v_cndmask_b32_e64 v38, 1.0, v37, s[14:15]
	v_exp_f32_e32 v121, v114
	v_or_b32_e32 v39, 9, v35
	v_cmp_lt_i32_e64 s[20:21], v39, v82
	v_or_b32_e32 v39, 10, v35
	v_add_f32_e32 v37, 1.0, v121
	v_rcp_f32_e32 v37, v37
	v_cmp_lt_i32_e64 s[22:23], v39, v82
	v_or_b32_e32 v39, 11, v35
	v_cmp_lt_i32_e64 s[24:25], v39, v82
	v_cndmask_b32_e64 v40, 1.0, v37, s[16:17]
	v_exp_f32_e32 v130, v89
	v_or_b32_e32 v39, 16, v35
	v_cmp_lt_i32_e64 s[26:27], v39, v82
	v_or_b32_e32 v39, 17, v35
	v_add_f32_e32 v37, 1.0, v130
	v_rcp_f32_e32 v37, v37
	v_cmp_lt_i32_e64 s[28:29], v39, v82
	v_or_b32_e32 v39, 18, v35
	v_cmp_lt_i32_e64 s[30:31], v39, v82
	v_cndmask_b32_e64 v42, 1.0, v37, s[18:19]
	v_exp_f32_e32 v131, v88
	v_or_b32_e32 v39, 19, v35
	v_cmp_lt_i32_e64 s[34:35], v39, v82
	v_or_b32_e32 v39, 24, v35
	v_add_f32_e32 v37, 1.0, v131
	v_rcp_f32_e32 v37, v37
	v_cmp_lt_i32_e64 s[36:37], v39, v82
	v_or_b32_e32 v39, 25, v35
	v_cmp_lt_i32_e64 s[38:39], v39, v82
	v_cndmask_b32_e64 v44, 1.0, v37, s[20:21]
	v_exp_f32_e32 v132, v86
	v_or_b32_e32 v39, 26, v35
	v_cmp_lt_i32_e64 s[40:41], v39, v82
	v_cmp_lt_i32_e32 vcc, v35, v82
	v_add_f32_e32 v37, 1.0, v132
	v_rcp_f32_e32 v37, v37
	v_or_b32_e32 v35, 27, v35
	v_cmp_lt_i32_e64 s[42:43], v35, v82
	v_xor_b32_e32 v35, 32, v238
	v_cndmask_b32_e64 v45, 1.0, v37, s[22:23]
	v_exp_f32_e32 v133, v87
	v_exp_f32_e32 v118, v117
	v_add_f32_e32 v37, 1.0, v133
	v_rcp_f32_e32 v37, v37
	v_exp_f32_e32 v119, v116
	v_add_f32_e32 v34, 1.0, v118
	v_rcp_f32_e32 v34, v34
	v_cndmask_b32_e64 v43, 1.0, v37, s[24:25]
	v_exp_f32_e32 v134, v90
	v_mul_f32_e32 v126, v44, v42
	v_mul_f32_e32 v127, v45, v43
	v_add_f32_e32 v36, 1.0, v119
	v_pk_mul_f32 v[126:127], v[126:127], v[126:127] op_sel:[0,1] op_sel_hi:[1,0]
	v_add_f32_e32 v37, 1.0, v134
	v_rcp_f32_e32 v37, v37
	v_rcp_f32_e32 v36, v36
	v_cndmask_b32_e32 v34, 1.0, v34, vcc
	v_cndmask_b32_e32 v118, 0, v118, vcc
	v_cndmask_b32_e64 v46, 1.0, v37, s[26:27]
	v_exp_f32_e32 v135, v91
	v_cndmask_b32_e64 v36, 1.0, v36, s[12:13]
	v_cndmask_b32_e64 v119, 0, v119, s[12:13]
	v_cndmask_b32_e64 v120, 0, v120, s[14:15]
	v_add_f32_e32 v37, 1.0, v135
	v_rcp_f32_e32 v37, v37
	v_cndmask_b32_e64 v121, 0, v121, s[16:17]
	s_mov_b64 s[12:13], 0
	v_cndmask_b32_e64 v48, 1.0, v37, s[28:29]
	v_exp_f32_e32 v136, v113
	s_nop 0
	v_add_f32_e32 v37, 1.0, v136
	v_rcp_f32_e32 v37, v37
	s_nop 0
	v_cndmask_b32_e64 v49, 1.0, v37, s[30:31]
	v_exp_f32_e32 v137, v112
	s_nop 0
	v_add_f32_e32 v37, 1.0, v137
	v_rcp_f32_e32 v37, v37
	s_nop 0
	v_cndmask_b32_e64 v47, 1.0, v37, s[34:35]
	v_exp_f32_e32 v138, v111
	v_mul_f32_e32 v128, v48, v46
	v_mul_f32_e32 v129, v49, v47
	v_add_f32_e32 v37, 1.0, v138
	v_rcp_f32_e32 v37, v37
	s_nop 0
	v_cndmask_b32_e64 v122, 1.0, v37, s[36:37]
	v_exp_f32_e32 v139, v110
	s_nop 0
	v_add_f32_e32 v37, 1.0, v139
	v_rcp_f32_e32 v37, v37
	s_nop 0
	v_cndmask_b32_e64 v124, 1.0, v37, s[38:39]
	v_exp_f32_e32 v140, v109
	s_nop 0
	v_add_f32_e32 v37, 1.0, v140
	v_rcp_f32_e32 v37, v37
	s_nop 0
	v_cndmask_b32_e64 v125, 1.0, v37, s[40:41]
	v_exp_f32_e32 v141, v85
	s_nop 0
	v_add_f32_e32 v37, 1.0, v141
	v_rcp_f32_e32 v37, v37
	s_nop 0
	v_cndmask_b32_e64 v123, 1.0, v37, s[42:43]
	v_and_b32_e32 v37, 64, v238
	v_add_u32_e32 v37, 64, v37
	v_cmp_lt_i32_e64 s[44:45], v35, v37
	s_nop 1
	v_cndmask_b32_e64 v35, v238, v35, s[44:45]
	v_lshlrev_b32_e32 v142, 2, v35
	v_mul_f32_e32 v35, v128, v129
	v_mul_f32_e32 v128, v124, v122
	v_mul_f32_e32 v129, v125, v123
	ds_bpermute_b32 v39, v142, v35
	v_mul_f32_e32 v41, v128, v129
	ds_bpermute_b32 v127, v142, v41
	ds_bpermute_b32 v37, v142, v126
	s_waitcnt lgkmcnt(1)
	v_mul_f32_e32 v41, v41, v127
	v_mul_f32_e32 v41, v108, v41
	v_mul_f32_e32 v128, v108, v127
	v_mul_f32_e32 v127, v41, v39
	v_mul_f32_e32 v39, v35, v39
	v_mov_b32_e32 v35, v126
	v_cndmask_b32_e64 v143, v108, v128, s[10:11]
	v_cndmask_b32_e64 v144, v41, v127, s[10:11]
	v_mul_f32_e32 v128, v38, v40
	v_mul_f32_e32 v129, v39, v41
	s_waitcnt lgkmcnt(0)
	v_mul_f32_e32 v126, v34, v36
	v_mul_f32_e32 v127, v35, v37
	v_mul_f32_e32 v35, v129, v37
	v_mul_f32_e32 v126, v126, v128
	v_mul_f32_e32 v127, v127, v129
	ds_bpermute_b32 v145, v142, v126
	v_cndmask_b32_e64 v35, v129, v35, s[10:11]
	v_cndmask_b32_e64 v129, 0, v131, s[20:21]
	v_cndmask_b32_e64 v131, 0, v133, s[24:25]
	v_cndmask_b32_e64 v133, 0, v135, s[28:29]
	s_waitcnt lgkmcnt(0)
	v_mul_f32_e32 v37, v127, v145
	v_cndmask_b32_e64 v135, 0, v137, s[34:35]
	v_cndmask_b32_e64 v137, 0, v139, s[38:39]
	v_cndmask_b32_e64 v139, 0, v141, s[42:43]
	v_mul_f32_e32 v141, v123, v143
	v_cndmask_b32_e64 v37, v127, v37, s[10:11]
	v_cndmask_b32_e64 v128, 0, v130, s[18:19]
	v_cndmask_b32_e64 v130, 0, v132, s[22:23]
	v_cndmask_b32_e64 v132, 0, v134, s[26:27]
	v_cndmask_b32_e64 v134, 0, v136, s[30:31]
	v_cndmask_b32_e64 v136, 0, v138, s[36:37]
	v_cndmask_b32_e64 v138, 0, v140, s[40:41]
	v_mul_f32_e32 v140, v125, v141
	v_mul_f32_e32 v125, v47, v144
	v_mul_f32_e32 v123, v124, v140
	v_mul_f32_e32 v124, v49, v125
	v_mul_f32_e32 v39, v40, v37
	v_mul_f32_e32 v143, v48, v124
	v_mul_f32_e32 v47, v43, v35
	v_mul_f32_e32 v38, v38, v39
	v_mul_f32_e32 v142, v46, v143
	v_mul_f32_e32 v46, v45, v47
	v_mul_f32_e32 v35, v36, v38
	v_mul_f32_e32 v43, v44, v46
	v_mul_f32_e32 v34, v34, v35
	v_mul_f32_e32 v122, v122, v123
	v_mul_f32_e32 v42, v42, v43
	v_mul_f32_e32 v48, v118, v34
	v_mul_f32_e32 v49, v119, v35
	v_mul_f32_e32 v118, v126, v145
	v_mul_f32_e32 v40, v130, v46
	v_mul_f32_e32 v41, v131, v47
	v_mul_f32_e32 v44, v128, v42
	v_mul_f32_e32 v45, v129, v43
	v_mul_f32_e32 v46, v120, v38
	v_mul_f32_e32 v47, v121, v39
	v_mul_f32_e32 v34, v134, v124
	v_mul_f32_e32 v35, v135, v125
	v_mul_f32_e32 v38, v132, v142
	v_mul_f32_e32 v39, v133, v143
	v_mul_f32_e32 v36, v138, v140
	v_mul_f32_e32 v37, v139, v141
	v_mul_f32_e32 v42, v136, v122
	v_mul_f32_e32 v43, v137, v123
	v_mul_f32_e32 v118, v118, v127
.LBB0_463:
	s_andn2_b64 vcc, exec, s[12:13]
	s_cbranch_vccnz .LBB0_465
	v_exp_f32_e32 v34, v117
	v_and_b32_e32 v39, 64, v238
	v_add_u32_e32 v39, 64, v39
	v_add_f32_e32 v35, 1.0, v34
	v_rcp_f32_e32 v36, v35
	v_exp_f32_e32 v35, v116
	s_nop 0
	v_add_f32_e32 v37, 1.0, v35
	v_rcp_f32_e32 v38, v37
	v_exp_f32_e32 v40, v115
	s_nop 0
	v_add_f32_e32 v37, 1.0, v40
	v_rcp_f32_e32 v42, v37
	v_exp_f32_e32 v41, v114
	s_nop 0
	v_add_f32_e32 v37, 1.0, v41
	v_rcp_f32_e32 v46, v37
	v_exp_f32_e32 v44, v89
	s_nop 0
	v_add_f32_e32 v37, 1.0, v44
	v_rcp_f32_e32 v48, v37
	v_exp_f32_e32 v45, v88
	s_nop 0
	v_add_f32_e32 v37, 1.0, v45
	v_rcp_f32_e32 v88, v37
	v_exp_f32_e32 v86, v86
	s_nop 0
	v_add_f32_e32 v37, 1.0, v86
	v_rcp_f32_e32 v49, v37
	v_exp_f32_e32 v87, v87
	s_nop 0
	v_add_f32_e32 v37, 1.0, v87
	v_rcp_f32_e32 v89, v37
	v_exp_f32_e32 v90, v90
	v_mul_f32_e32 v124, v48, v88
	v_mul_f32_e32 v125, v49, v89
	s_nop 0
	v_pk_mul_f32 v[124:125], v[124:125], v[124:125] op_sel:[0,1] op_sel_hi:[1,0]
	v_add_f32_e32 v37, 1.0, v90
	v_rcp_f32_e32 v114, v37
	v_exp_f32_e32 v91, v91
	s_nop 0
	v_add_f32_e32 v37, 1.0, v91
	v_rcp_f32_e32 v116, v37
	v_exp_f32_e32 v118, v113
	s_nop 0
	v_add_f32_e32 v37, 1.0, v118
	v_rcp_f32_e32 v115, v37
	v_exp_f32_e32 v119, v112
	s_nop 0
	v_add_f32_e32 v37, 1.0, v119
	v_rcp_f32_e32 v117, v37
	v_exp_f32_e32 v112, v111
	v_mul_f32_e32 v126, v114, v116
	v_mul_f32_e32 v127, v115, v117
	v_add_f32_e32 v37, 1.0, v112
	v_rcp_f32_e32 v120, v37
	v_exp_f32_e32 v113, v110
	s_nop 0
	v_add_f32_e32 v37, 1.0, v113
	v_rcp_f32_e32 v110, v37
	v_exp_f32_e32 v122, v109
	s_nop 0
	v_add_f32_e32 v37, 1.0, v122
	v_rcp_f32_e32 v121, v37
	v_exp_f32_e32 v123, v85
	s_nop 0
	v_add_f32_e32 v37, 1.0, v123
	v_rcp_f32_e32 v111, v37
	v_xor_b32_e32 v37, 32, v238
	v_cmp_lt_i32_e32 vcc, v37, v39
	s_nop 1
	v_cndmask_b32_e32 v37, v238, v37, vcc
	v_lshlrev_b32_e32 v85, 2, v37
	v_mul_f32_e32 v37, v126, v127
	v_mul_f32_e32 v126, v120, v110
	v_mul_f32_e32 v127, v121, v111
	ds_bpermute_b32 v43, v85, v37
	v_mul_f32_e32 v47, v126, v127
	ds_bpermute_b32 v109, v85, v47
	ds_bpermute_b32 v39, v85, v124
	s_waitcnt lgkmcnt(1)
	v_mul_f32_e32 v47, v47, v109
	v_mul_f32_e32 v125, v108, v109
	v_mul_f32_e32 v47, v108, v47
	v_cndmask_b32_e64 v126, v108, v125, s[10:11]
	v_mul_f32_e32 v108, v47, v43
	v_mul_f32_e32 v43, v37, v43
	v_mov_b32_e32 v37, v124
	v_cndmask_b32_e64 v127, v47, v108, s[10:11]
	v_mul_f32_e32 v108, v42, v46
	v_mul_f32_e32 v109, v43, v47
	s_waitcnt lgkmcnt(0)
	v_mul_f32_e32 v124, v36, v38
	v_mul_f32_e32 v125, v37, v39
	v_mul_f32_e32 v37, v109, v39
	v_mul_f32_e32 v124, v124, v108
	v_mul_f32_e32 v125, v125, v109
	ds_bpermute_b32 v85, v85, v124
	v_cndmask_b32_e64 v37, v109, v37, s[10:11]
	v_mul_f32_e32 v109, v111, v126
	v_mul_f32_e32 v108, v121, v109
	v_mul_f32_e32 v111, v110, v108
	s_waitcnt lgkmcnt(0)
	v_mul_f32_e32 v39, v125, v85
	v_cndmask_b32_e64 v39, v125, v39, s[10:11]
	v_mul_f32_e32 v121, v117, v127
	v_mul_f32_e32 v110, v120, v111
	v_mul_f32_e32 v120, v115, v121
	v_mul_f32_e32 v117, v89, v37
	v_mul_f32_e32 v43, v46, v39
	v_mul_f32_e32 v115, v116, v120
	v_mul_f32_e32 v116, v49, v117
	v_mul_f32_e32 v42, v42, v43
	v_mul_f32_e32 v89, v88, v116
	v_mul_f32_e32 v37, v38, v42
	v_mul_f32_e32 v114, v114, v115
	v_mul_f32_e32 v88, v48, v89
	v_mul_f32_e32 v36, v36, v37
	v_mul_f32_e32 v85, v124, v85
	v_mul_f32_e32 v48, v34, v36
	v_mul_f32_e32 v49, v35, v37
	v_mul_f32_e32 v46, v40, v42
	v_mul_f32_e32 v47, v41, v43
	v_mul_f32_e32 v44, v44, v88
	v_mul_f32_e32 v45, v45, v89
	v_mul_f32_e32 v40, v86, v116
	v_mul_f32_e32 v41, v87, v117
	v_mul_f32_e32 v38, v90, v114
	v_mul_f32_e32 v39, v91, v115
	v_mul_f32_e32 v34, v118, v120
	v_mul_f32_e32 v35, v119, v121
	v_mul_f32_e32 v42, v112, v110
	v_mul_f32_e32 v43, v113, v111
	v_mul_f32_e32 v36, v122, v108
	v_mul_f32_e32 v37, v123, v109
	v_mul_f32_e32 v118, v85, v125

.LBB0_707:
	s_ashr_i32 s16, s53, 3
	v_mov_b32_e32 v230, v232
	s_ashr_i32 s17, s16, 31
	v_readfirstlane_b32 s4, v230
	s_lshl_b32 s5, s53, 8
	s_ashr_i32 s4, s4, 6
	s_lshl_b64 s[18:19], s[16:17], 11
	s_and_b32 s5, s5, 0x700
	v_and_b32_e32 v234, 31, v230
	s_or_b32 s5, s18, s5
	s_lshl_b32 s18, s4, 5
	s_lshl_b64 s[16:17], s[16:17], 20
	v_or_b32_e32 v2, s5, v234
	s_add_u32 s5, s22, s16
	v_mov_b32_e32 v3, s19
	s_addc_u32 s19, s23, s17
	s_lshl_b32 s16, s52, 8
	v_bfe_u32 v231, v230, 5, 1
	s_ashr_i32 s17, s16, 31
	v_lshrrev_b32_e32 v6, 5, v230
	s_lshl_b64 s[16:17], s[16:17], 1
	v_or_b32_e32 v4, s18, v231
	s_add_u32 s20, s5, s16
	v_bitop3_b32 v0, v6, v230, 1 bitop3:0x6c
	v_ashrrev_i32_e32 v5, 31, v4
	s_addc_u32 s21, s19, s17
	s_lshl_b32 s19, s4, 4
	v_lshlrev_b64 v[4:5], 12, v[4:5]
	v_lshlrev_b32_e32 v0, 4, v0
	v_lshl_add_u64 v[156:157], s[20:21], 0, v[4:5]
	v_and_b32_e32 v0, 0x1f0, v0
	s_lshl_b32 s4, s19, 10
	s_barrier
	v_lshl_add_u64 v[4:5], v[156:157], 0, v[0:1]
	s_add_i32 s24, s4, 0
	s_mov_b32 s4, m0
	s_mov_b32 m0, s24
	s_nop 0
	global_load_lds_dwordx4 v[4:5], off
	s_mov_b32 m0, s4
	s_or_b32 s4, s19, 1
	s_lshl_b32 s5, s4, 1
	v_or_b32_e32 v158, s5, v231
	v_bitop3_b32 v0, s5, v230, v231 bitop3:0x36
	v_ashrrev_i32_e32 v159, 31, v158
	v_lshlrev_b64 v[4:5], 12, v[158:159]
	v_lshlrev_b32_e32 v0, 4, v0
	v_lshl_add_u64 v[160:161], s[20:21], 0, v[4:5]
	v_and_b32_e32 v0, 0x1f0, v0
	s_lshl_b32 s4, s4, 10
	v_lshl_add_u64 v[4:5], v[160:161], 0, v[0:1]
	s_add_i32 s25, s4, 0
	s_mov_b32 s4, m0
	s_mov_b32 m0, s25
	s_nop 0
	global_load_lds_dwordx4 v[4:5], off
	s_mov_b32 m0, s4
	s_or_b32 s4, s19, 2
	s_lshl_b32 s5, s4, 1
	v_or_b32_e32 v162, s5, v231
	v_bitop3_b32 v0, s5, v230, v231 bitop3:0x36
	v_ashrrev_i32_e32 v163, 31, v162
	v_lshlrev_b64 v[4:5], 12, v[162:163]
	v_lshlrev_b32_e32 v0, 4, v0
	v_lshl_add_u64 v[164:165], s[20:21], 0, v[4:5]
	v_and_b32_e32 v0, 0x1f0, v0
	s_lshl_b32 s4, s4, 10
	v_lshl_add_u64 v[4:5], v[164:165], 0, v[0:1]
	s_add_i32 s26, s4, 0
	s_mov_b32 s4, m0
	s_mov_b32 m0, s26
	s_nop 0
	global_load_lds_dwordx4 v[4:5], off
	s_mov_b32 m0, s4
	s_or_b32 s4, s19, 3
	s_lshl_b32 s5, s4, 1
	v_or_b32_e32 v166, s5, v231
	v_bitop3_b32 v0, s5, v230, v231 bitop3:0x36
	v_ashrrev_i32_e32 v167, 31, v166
	v_lshlrev_b64 v[4:5], 12, v[166:167]
	v_lshlrev_b32_e32 v0, 4, v0
	v_lshl_add_u64 v[168:169], s[20:21], 0, v[4:5]
	v_and_b32_e32 v0, 0x1f0, v0
	s_lshl_b32 s4, s4, 10
	v_lshl_add_u64 v[4:5], v[168:169], 0, v[0:1]
	s_add_i32 s27, s4, 0
	s_mov_b32 s4, m0
	s_mov_b32 m0, s27
	s_nop 0
	global_load_lds_dwordx4 v[4:5], off
	s_mov_b32 m0, s4
	s_or_b32 s4, s19, 4
	s_lshl_b32 s5, s4, 1
	v_or_b32_e32 v170, s5, v231
	v_bitop3_b32 v0, s5, v230, v231 bitop3:0x36
	v_ashrrev_i32_e32 v171, 31, v170
	v_lshlrev_b64 v[4:5], 12, v[170:171]
	v_lshlrev_b32_e32 v0, 4, v0
	v_lshl_add_u64 v[172:173], s[20:21], 0, v[4:5]
	v_and_b32_e32 v0, 0x1f0, v0
	s_lshl_b32 s4, s4, 10
	v_lshl_add_u64 v[4:5], v[172:173], 0, v[0:1]
	s_add_i32 s28, s4, 0
	s_mov_b32 s4, m0
	s_mov_b32 m0, s28
	s_nop 0
	global_load_lds_dwordx4 v[4:5], off
	s_mov_b32 m0, s4
	s_or_b32 s4, s19, 5
	s_lshl_b32 s5, s4, 1
	v_or_b32_e32 v174, s5, v231
	v_bitop3_b32 v0, s5, v230, v231 bitop3:0x36
	v_ashrrev_i32_e32 v175, 31, v174
	v_lshlrev_b64 v[4:5], 12, v[174:175]
	v_lshlrev_b32_e32 v0, 4, v0
	v_lshl_add_u64 v[176:177], s[20:21], 0, v[4:5]
	v_and_b32_e32 v0, 0x1f0, v0
	s_lshl_b32 s4, s4, 10
	v_lshl_add_u64 v[4:5], v[176:177], 0, v[0:1]
	s_add_i32 s29, s4, 0
	s_mov_b32 s4, m0
	s_mov_b32 m0, s29
	s_nop 0
	global_load_lds_dwordx4 v[4:5], off
	s_mov_b32 m0, s4
	s_or_b32 s4, s19, 6
	s_lshl_b32 s5, s4, 1
	v_or_b32_e32 v178, s5, v231
	v_bitop3_b32 v0, s5, v230, v231 bitop3:0x36
	v_ashrrev_i32_e32 v179, 31, v178
	v_lshlrev_b64 v[4:5], 12, v[178:179]
	v_lshlrev_b32_e32 v0, 4, v0
	v_lshl_add_u64 v[180:181], s[20:21], 0, v[4:5]
	v_and_b32_e32 v0, 0x1f0, v0
	s_lshl_b32 s4, s4, 10
	v_lshl_add_u64 v[4:5], v[180:181], 0, v[0:1]
	s_add_i32 s30, s4, 0
	s_mov_b32 s4, m0
	s_mov_b32 m0, s30
	s_nop 0
	global_load_lds_dwordx4 v[4:5], off
	s_mov_b32 m0, s4
	s_or_b32 s4, s19, 7
	s_lshl_b32 s5, s4, 1
	v_or_b32_e32 v182, s5, v231
	v_bitop3_b32 v0, s5, v230, v231 bitop3:0x36
	v_ashrrev_i32_e32 v183, 31, v182
	v_lshlrev_b64 v[4:5], 12, v[182:183]
	v_lshlrev_b32_e32 v0, 4, v0
	v_lshl_add_u64 v[184:185], s[20:21], 0, v[4:5]
	v_and_b32_e32 v0, 0x1f0, v0
	s_lshl_b32 s4, s4, 10
	v_lshl_add_u64 v[4:5], v[184:185], 0, v[0:1]
	s_add_i32 s31, s4, 0
	s_mov_b32 s4, m0
	s_mov_b32 m0, s31
	s_nop 0
	global_load_lds_dwordx4 v[4:5], off
	s_mov_b32 m0, s4
	s_or_b32 s4, s19, 8
	s_lshl_b32 s5, s4, 1
	v_or_b32_e32 v186, s5, v231
	v_bitop3_b32 v0, s5, v230, v231 bitop3:0x36
	v_ashrrev_i32_e32 v187, 31, v186
	v_lshlrev_b64 v[4:5], 12, v[186:187]
	v_lshlrev_b32_e32 v0, 4, v0
	v_lshl_add_u64 v[188:189], s[20:21], 0, v[4:5]
	v_and_b32_e32 v0, 0x1f0, v0
	s_lshl_b32 s4, s4, 10
	v_lshl_add_u64 v[4:5], v[188:189], 0, v[0:1]
	s_add_i32 s34, s4, 0
	s_mov_b32 s4, m0
	s_mov_b32 m0, s34
	s_nop 0
	global_load_lds_dwordx4 v[4:5], off
	s_mov_b32 m0, s4
	s_or_b32 s4, s19, 9
	s_lshl_b32 s5, s4, 1
	v_or_b32_e32 v190, s5, v231
	v_bitop3_b32 v0, s5, v230, v231 bitop3:0x36
	v_ashrrev_i32_e32 v191, 31, v190
	v_lshlrev_b64 v[4:5], 12, v[190:191]
	v_lshlrev_b32_e32 v0, 4, v0
	v_lshl_add_u64 v[192:193], s[20:21], 0, v[4:5]
	v_and_b32_e32 v0, 0x1f0, v0
	s_lshl_b32 s4, s4, 10
	v_lshl_add_u64 v[4:5], v[192:193], 0, v[0:1]
	s_add_i32 s35, s4, 0
	s_mov_b32 s4, m0
	s_mov_b32 m0, s35
	s_nop 0
	global_load_lds_dwordx4 v[4:5], off
	s_mov_b32 m0, s4
	s_or_b32 s4, s19, 10
	s_lshl_b32 s5, s4, 1
	v_or_b32_e32 v202, s5, v231
	v_bitop3_b32 v0, s5, v230, v231 bitop3:0x36
	v_ashrrev_i32_e32 v203, 31, v202
	v_lshlrev_b64 v[4:5], 12, v[202:203]
	v_lshlrev_b32_e32 v0, 4, v0
	v_lshl_add_u64 v[204:205], s[20:21], 0, v[4:5]
	v_and_b32_e32 v0, 0x1f0, v0
	s_lshl_b32 s4, s4, 10
	v_lshl_add_u64 v[4:5], v[204:205], 0, v[0:1]
	s_add_i32 s36, s4, 0
	s_mov_b32 s4, m0
	s_mov_b32 m0, s36
	s_nop 0
	global_load_lds_dwordx4 v[4:5], off
	s_mov_b32 m0, s4
	s_or_b32 s4, s19, 11
	s_lshl_b32 s5, s4, 1
	v_or_b32_e32 v206, s5, v231
	v_bitop3_b32 v0, s5, v230, v231 bitop3:0x36
	v_ashrrev_i32_e32 v207, 31, v206
	v_lshlrev_b64 v[4:5], 12, v[206:207]
	v_lshlrev_b32_e32 v0, 4, v0
	v_lshl_add_u64 v[208:209], s[20:21], 0, v[4:5]
	v_and_b32_e32 v0, 0x1f0, v0
	s_lshl_b32 s4, s4, 10
	v_lshl_add_u64 v[4:5], v[208:209], 0, v[0:1]
	s_add_i32 s37, s4, 0
	s_mov_b32 s4, m0
	s_mov_b32 m0, s37
	s_nop 0
	global_load_lds_dwordx4 v[4:5], off
	s_mov_b32 m0, s4
	s_or_b32 s4, s19, 12
	s_lshl_b32 s5, s4, 1
	v_or_b32_e32 v210, s5, v231
	v_bitop3_b32 v0, s5, v230, v231 bitop3:0x36
	v_ashrrev_i32_e32 v211, 31, v210
	v_lshlrev_b64 v[4:5], 12, v[210:211]
	v_lshlrev_b32_e32 v0, 4, v0
	v_lshl_add_u64 v[212:213], s[20:21], 0, v[4:5]
	v_and_b32_e32 v0, 0x1f0, v0
	s_lshl_b32 s4, s4, 10
	v_lshl_add_u64 v[4:5], v[212:213], 0, v[0:1]
	s_add_i32 s38, s4, 0
	s_mov_b32 s4, m0
	s_mov_b32 m0, s38
	s_nop 0
	global_load_lds_dwordx4 v[4:5], off
	s_mov_b32 m0, s4
	s_or_b32 s4, s19, 13
	s_lshl_b32 s5, s4, 1
	v_or_b32_e32 v214, s5, v231
	v_bitop3_b32 v0, s5, v230, v231 bitop3:0x36
	v_ashrrev_i32_e32 v215, 31, v214
	v_lshlrev_b64 v[4:5], 12, v[214:215]
	v_lshlrev_b32_e32 v0, 4, v0
	v_lshl_add_u64 v[216:217], s[20:21], 0, v[4:5]
	v_and_b32_e32 v0, 0x1f0, v0
	s_lshl_b32 s4, s4, 10
	v_lshl_add_u64 v[4:5], v[216:217], 0, v[0:1]
	s_add_i32 s39, s4, 0
	s_mov_b32 s4, m0
	s_mov_b32 m0, s39
	s_nop 0
	global_load_lds_dwordx4 v[4:5], off
	s_mov_b32 m0, s4
	s_or_b32 s4, s19, 14
	s_lshl_b32 s5, s4, 1
	v_or_b32_e32 v218, s5, v231
	v_bitop3_b32 v0, s5, v230, v231 bitop3:0x36
	v_ashrrev_i32_e32 v219, 31, v218
	v_lshlrev_b64 v[4:5], 12, v[218:219]
	v_lshlrev_b32_e32 v0, 4, v0
	v_lshl_add_u64 v[220:221], s[20:21], 0, v[4:5]
	v_and_b32_e32 v0, 0x1f0, v0
	s_lshl_b32 s4, s4, 10
	v_lshl_add_u64 v[4:5], v[220:221], 0, v[0:1]
	s_add_i32 s40, s4, 0
	s_mov_b32 s4, m0
	s_mov_b32 m0, s40
	s_nop 0
	global_load_lds_dwordx4 v[4:5], off
	s_mov_b32 m0, s4
	s_or_b32 s4, s19, 15
	s_lshl_b32 s5, s4, 1
	v_or_b32_e32 v222, s5, v231
	v_bitop3_b32 v0, s5, v230, v231 bitop3:0x36
	v_ashrrev_i32_e32 v223, 31, v222
	s_ashr_i32 s19, s18, 31
	v_lshlrev_b64 v[4:5], 12, v[222:223]
	v_lshlrev_b32_e32 v0, 4, v0
	v_lshl_add_u64 v[226:227], v[2:3], 0, s[18:19]
	v_lshl_add_u64 v[224:225], s[20:21], 0, v[4:5]
	v_and_b32_e32 v0, 0x1f0, v0
	v_lshlrev_b64 v[154:155], 11, v[226:227]
	v_lshl_add_u64 v[4:5], v[224:225], 0, v[0:1]
	s_lshl_b32 s4, s4, 10
	v_lshl_add_u64 v[2:3], s[8:9], 0, v[154:155]
	s_add_i32 s20, s4, 0
	s_mov_b32 s4, m0
	s_mov_b32 m0, s20
	s_nop 0
	global_load_lds_dwordx4 v[4:5], off
	s_mov_b32 m0, s4
	v_lshl_add_u64 v[2:3], v[2:3], 0, s[16:17]
	v_lshlrev_b32_e32 v4, 4, v231
	v_mov_b32_e32 v5, v1
	v_lshl_add_u64 v[228:229], v[2:3], 0, v[4:5]
	s_waitcnt vmcnt(0)
	s_barrier
	global_load_dwordx4 v[18:21], v[228:229], off
	global_load_dwordx4 v[142:145], v[228:229], off offset:32
	v_bitop3_b32 v2, v6, v234, 1 bitop3:0x6c
	v_lshlrev_b32_e32 v0, 9, v234
	v_lshlrev_b32_e32 v2, 4, v2
	v_add3_u32 v26, 0, v2, v0
	ds_read_b128 v[2:5], v26
	global_load_dwordx4 v[138:141], v[228:229], off offset:64
	global_load_dwordx4 v[134:137], v[228:229], off offset:96
	s_waitcnt vmcnt(3) lgkmcnt(0)
	v_mfma_f32_32x32x16_bf16 v[66:81], v[2:5], v[18:21], 0
	ds_read_b128 v[2:5], v26 offset:16384
	global_load_dwordx4 v[130:133], v[228:229], off offset:128
	global_load_dwordx4 v[146:149], v[228:229], off offset:160
	v_add_u32_e32 v22, 0x14000, v26
	s_lshl_b32 s18, s52, 2
	s_ashr_i32 s19, s18, 31
	ds_read_b128 v[22:25], v22
	s_waitcnt lgkmcnt(1)
	v_mfma_f32_32x32x16_bf16 v[82:97], v[2:5], v[18:21], 0
	ds_read_b128 v[2:5], v26 offset:32768
	s_waitcnt lgkmcnt(0)
	v_mfma_f32_32x32x16_bf16 v[98:113], v[2:5], v[18:21], 0
	ds_read_b128 v[2:5], v26 offset:49152
	s_waitcnt lgkmcnt(0)
	v_mfma_f32_32x32x16_bf16 v[114:129], v[2:5], v[18:21], 0
	v_bitop3_b32 v2, v231, v234, 2 bitop3:0x36
	v_lshlrev_b32_e32 v2, 4, v2
	v_add3_u32 v151, 0, v2, v0
	ds_read_b128 v[2:5], v151
	v_add_u32_e32 v27, 0x14000, v151
	s_waitcnt vmcnt(4) lgkmcnt(0)
	v_mfma_f32_32x32x16_bf16 v[66:81], v[2:5], v[142:145], v[66:81]
	ds_read_b128 v[2:5], v151 offset:16384
	s_waitcnt lgkmcnt(0)
	v_mfma_f32_32x32x16_bf16 v[82:97], v[2:5], v[142:145], v[82:97]
	ds_read_b128 v[2:5], v151 offset:32768
	s_waitcnt lgkmcnt(0)
	v_mfma_f32_32x32x16_bf16 v[98:113], v[2:5], v[142:145], v[98:113]
	ds_read_b128 v[2:5], v151 offset:49152
	s_waitcnt lgkmcnt(0)
	v_mfma_f32_32x32x16_bf16 v[114:129], v[2:5], v[142:145], v[114:129]
	v_bitop3_b32 v2, v231, v234, 4 bitop3:0x36
	v_lshlrev_b32_e32 v2, 4, v2
	v_add3_u32 v152, 0, v2, v0
	ds_read_b128 v[2:5], v152
	s_waitcnt vmcnt(3) lgkmcnt(0)
	v_mfma_f32_32x32x16_bf16 v[66:81], v[2:5], v[138:141], v[66:81]
	ds_read_b128 v[2:5], v152 offset:16384
	s_waitcnt lgkmcnt(0)
	v_mfma_f32_32x32x16_bf16 v[82:97], v[2:5], v[138:141], v[82:97]
	ds_read_b128 v[2:5], v152 offset:32768
	s_waitcnt lgkmcnt(0)
	v_mfma_f32_32x32x16_bf16 v[98:113], v[2:5], v[138:141], v[98:113]
	ds_read_b128 v[2:5], v152 offset:49152
	s_waitcnt lgkmcnt(0)
	v_mfma_f32_32x32x16_bf16 v[114:129], v[2:5], v[138:141], v[114:129]
	v_bitop3_b32 v2, v231, v234, 6 bitop3:0x36
	v_lshlrev_b32_e32 v2, 4, v2
	v_add3_u32 v150, 0, v2, v0
	ds_read_b128 v[2:5], v150
	s_waitcnt vmcnt(2) lgkmcnt(0)
	v_mfma_f32_32x32x16_bf16 v[66:81], v[2:5], v[134:137], v[66:81]
	ds_read_b128 v[2:5], v150 offset:16384
	s_waitcnt lgkmcnt(0)
	v_mfma_f32_32x32x16_bf16 v[82:97], v[2:5], v[134:137], v[82:97]
	ds_read_b128 v[2:5], v150 offset:32768
	s_waitcnt lgkmcnt(0)
	v_mfma_f32_32x32x16_bf16 v[98:113], v[2:5], v[134:137], v[98:113]
	ds_read_b128 v[2:5], v150 offset:49152
	s_waitcnt lgkmcnt(0)
	v_mfma_f32_32x32x16_bf16 v[114:129], v[2:5], v[134:137], v[114:129]
	v_bitop3_b32 v2, v231, v234, 8 bitop3:0x36
	v_lshlrev_b32_e32 v2, 4, v2
	v_add3_u32 v159, 0, v2, v0
	ds_read_b128 v[2:5], v159
	s_waitcnt vmcnt(1) lgkmcnt(0)
	v_mfma_f32_32x32x16_bf16 v[66:81], v[2:5], v[130:133], v[66:81]
	ds_read_b128 v[2:5], v159 offset:16384
	s_waitcnt lgkmcnt(0)
	v_mfma_f32_32x32x16_bf16 v[82:97], v[2:5], v[130:133], v[82:97]
	ds_read_b128 v[2:5], v159 offset:32768
	s_waitcnt lgkmcnt(0)
	v_mfma_f32_32x32x16_bf16 v[98:113], v[2:5], v[130:133], v[98:113]
	ds_read_b128 v[2:5], v159 offset:49152
	s_waitcnt lgkmcnt(0)
	v_mfma_f32_32x32x16_bf16 v[114:129], v[2:5], v[130:133], v[114:129]
	v_add_u32_e32 v2, 0x10000, v26
	ds_read_b128 v[2:5], v2
	v_mfma_f32_32x32x16_bf16 v[50:65], v[22:25], v[18:21], 0
	v_add_u32_e32 v22, 0x18000, v26
	ds_read_b128 v[22:25], v22
	v_add_u32_e32 v26, 0x1c000, v26
	s_waitcnt lgkmcnt(0)
	v_mfma_f32_32x32x16_bf16 v[34:49], v[22:25], v[18:21], 0
	v_add_u32_e32 v22, 0x10000, v151
	ds_read_b128 v[22:25], v22
	v_mfma_f32_32x32x16_bf16 v[2:17], v[2:5], v[18:21], 0
	s_waitcnt lgkmcnt(0)
	v_mfma_f32_32x32x16_bf16 v[2:17], v[22:25], v[142:145], v[2:17]
	ds_read_b128 v[22:25], v27
	s_waitcnt lgkmcnt(0)
	v_mfma_f32_32x32x16_bf16 v[50:65], v[22:25], v[142:145], v[50:65]
	v_add_u32_e32 v22, 0x18000, v151
	ds_read_b128 v[22:25], v22
	v_add_u32_e32 v151, 0x1c000, v151
	ds_read_b128 v[242:245], v151
	v_add_u32_e32 v151, 0x14000, v152
	s_waitcnt lgkmcnt(1)
	v_mfma_f32_32x32x16_bf16 v[34:49], v[22:25], v[142:145], v[34:49]
	ds_read_b128 v[22:25], v26
	s_waitcnt lgkmcnt(0)
	v_mfma_f32_32x32x16_bf16 v[18:33], v[22:25], v[18:21], 0
	v_mfma_f32_32x32x16_bf16 v[18:33], v[242:245], v[142:145], v[18:33]
	v_bitop3_b32 v142, v231, v234, 10 bitop3:0x36
	v_lshlrev_b32_e32 v142, 4, v142
	v_add3_u32 v163, 0, v142, v0
	ds_read_b128 v[142:145], v163
	s_waitcnt vmcnt(0) lgkmcnt(0)
	v_mfma_f32_32x32x16_bf16 v[66:81], v[142:145], v[146:149], v[66:81]
	ds_read_b128 v[142:145], v163 offset:16384
	s_waitcnt lgkmcnt(0)
	v_mfma_f32_32x32x16_bf16 v[82:97], v[142:145], v[146:149], v[82:97]
	ds_read_b128 v[142:145], v163 offset:32768
	s_waitcnt lgkmcnt(0)
	v_mfma_f32_32x32x16_bf16 v[98:113], v[142:145], v[146:149], v[98:113]
	ds_read_b128 v[142:145], v163 offset:49152
	s_waitcnt lgkmcnt(0)
	v_mfma_f32_32x32x16_bf16 v[114:129], v[142:145], v[146:149], v[114:129]
	v_add_u32_e32 v142, 0x10000, v152
	ds_read_b128 v[142:145], v142
	s_waitcnt lgkmcnt(0)
	v_mfma_f32_32x32x16_bf16 v[2:17], v[142:145], v[138:141], v[2:17]
	ds_read_b128 v[142:145], v151
	v_add_u32_e32 v151, 0x1c000, v152
	ds_read_b128 v[242:245], v151
	v_add_u32_e32 v151, 0x14000, v150
	s_waitcnt lgkmcnt(1)
	v_mfma_f32_32x32x16_bf16 v[50:65], v[142:145], v[138:141], v[50:65]
	v_add_u32_e32 v142, 0x18000, v152
	ds_read_b128 v[142:145], v142
	s_waitcnt lgkmcnt(0)
	v_mfma_f32_32x32x16_bf16 v[34:49], v[142:145], v[138:141], v[34:49]
	global_load_dwordx4 v[142:145], v[228:229], off offset:192
	v_mfma_f32_32x32x16_bf16 v[18:33], v[242:245], v[138:141], v[18:33]
	v_bitop3_b32 v138, v231, v234, 12 bitop3:0x36
	v_lshlrev_b32_e32 v138, 4, v138
	v_add3_u32 v167, 0, v138, v0
	ds_read_b128 v[138:141], v167
	s_waitcnt vmcnt(0) lgkmcnt(0)
	v_mfma_f32_32x32x16_bf16 v[66:81], v[138:141], v[142:145], v[66:81]
	ds_read_b128 v[138:141], v167 offset:16384
	s_waitcnt lgkmcnt(0)
	v_mfma_f32_32x32x16_bf16 v[82:97], v[138:141], v[142:145], v[82:97]
	ds_read_b128 v[138:141], v167 offset:32768
	s_waitcnt lgkmcnt(0)
	v_mfma_f32_32x32x16_bf16 v[98:113], v[138:141], v[142:145], v[98:113]
	ds_read_b128 v[138:141], v167 offset:49152
	s_waitcnt lgkmcnt(0)
	v_mfma_f32_32x32x16_bf16 v[114:129], v[138:141], v[142:145], v[114:129]
	v_add_u32_e32 v138, 0x10000, v150
	ds_read_b128 v[138:141], v138
	s_waitcnt lgkmcnt(0)
	v_mfma_f32_32x32x16_bf16 v[2:17], v[138:141], v[134:137], v[2:17]
	ds_read_b128 v[138:141], v151
	s_waitcnt lgkmcnt(0)
	v_mfma_f32_32x32x16_bf16 v[50:65], v[138:141], v[134:137], v[50:65]
	v_add_u32_e32 v138, 0x18000, v150
	ds_read_b128 v[138:141], v138
	v_add_u32_e32 v150, 0x1c000, v150
	ds_read_b128 v[150:153], v150
	s_waitcnt lgkmcnt(1)
	v_mfma_f32_32x32x16_bf16 v[34:49], v[138:141], v[134:137], v[34:49]
	global_load_dwordx4 v[138:141], v[228:229], off offset:224
	s_waitcnt lgkmcnt(0)
	v_mfma_f32_32x32x16_bf16 v[18:33], v[150:153], v[134:137], v[18:33]
	v_bitop3_b32 v134, v231, v234, 14 bitop3:0x36
	v_lshlrev_b32_e32 v134, 4, v134
	v_add3_u32 v171, 0, v134, v0
	ds_read_b128 v[134:137], v171
	v_add_u32_e32 v150, 0x14000, v159
	s_waitcnt vmcnt(0) lgkmcnt(0)
	v_mfma_f32_32x32x16_bf16 v[66:81], v[134:137], v[138:141], v[66:81]
	ds_read_b128 v[134:137], v171 offset:16384
	s_waitcnt lgkmcnt(0)
	v_mfma_f32_32x32x16_bf16 v[82:97], v[134:137], v[138:141], v[82:97]
	ds_read_b128 v[134:137], v171 offset:32768
	s_waitcnt lgkmcnt(0)
	v_mfma_f32_32x32x16_bf16 v[98:113], v[134:137], v[138:141], v[98:113]
	ds_read_b128 v[134:137], v171 offset:49152
	s_waitcnt lgkmcnt(0)
	v_mfma_f32_32x32x16_bf16 v[114:129], v[134:137], v[138:141], v[114:129]
	v_add_u32_e32 v134, 0x10000, v159
	ds_read_b128 v[134:137], v134
	s_waitcnt lgkmcnt(0)
	v_mfma_f32_32x32x16_bf16 v[2:17], v[134:137], v[130:133], v[2:17]
	ds_read_b128 v[134:137], v150
	global_load_dwordx4 v[150:153], v[228:229], off offset:256
	s_waitcnt lgkmcnt(0)
	v_mfma_f32_32x32x16_bf16 v[50:65], v[134:137], v[130:133], v[50:65]
	v_add_u32_e32 v134, 0x18000, v159
	ds_read_b128 v[134:137], v134
	s_waitcnt lgkmcnt(0)
	v_mfma_f32_32x32x16_bf16 v[34:49], v[134:137], v[130:133], v[34:49]
	v_add_u32_e32 v134, 0x1c000, v159
	ds_read_b128 v[134:137], v134
	s_waitcnt lgkmcnt(0)
	v_mfma_f32_32x32x16_bf16 v[18:33], v[134:137], v[130:133], v[18:33]
	v_bitop3_b32 v130, v231, v234, 16 bitop3:0x36
	v_lshlrev_b32_e32 v130, 4, v130
	v_add3_u32 v159, 0, v130, v0
	ds_read_b128 v[130:133], v159
	v_add_u32_e32 v134, 0x14000, v163
	s_waitcnt vmcnt(0) lgkmcnt(0)
	v_mfma_f32_32x32x16_bf16 v[66:81], v[130:133], v[150:153], v[66:81]
	ds_read_b128 v[130:133], v159 offset:16384
	s_waitcnt lgkmcnt(0)
	v_mfma_f32_32x32x16_bf16 v[82:97], v[130:133], v[150:153], v[82:97]
	ds_read_b128 v[130:133], v159 offset:32768
	s_waitcnt lgkmcnt(0)
	v_mfma_f32_32x32x16_bf16 v[98:113], v[130:133], v[150:153], v[98:113]
	ds_read_b128 v[130:133], v159 offset:49152
	s_waitcnt lgkmcnt(0)
	v_mfma_f32_32x32x16_bf16 v[114:129], v[130:133], v[150:153], v[114:129]
	v_add_u32_e32 v130, 0x10000, v163
	ds_read_b128 v[130:133], v130
	s_waitcnt lgkmcnt(0)
	v_mfma_f32_32x32x16_bf16 v[2:17], v[130:133], v[146:149], v[2:17]
	ds_read_b128 v[130:133], v134
	v_add_u32_e32 v134, 0x1c000, v163
	ds_read_b128 v[134:137], v134
	s_waitcnt lgkmcnt(1)
	v_mfma_f32_32x32x16_bf16 v[50:65], v[130:133], v[146:149], v[50:65]
	v_add_u32_e32 v130, 0x18000, v163
	ds_read_b128 v[130:133], v130
	s_waitcnt lgkmcnt(0)
	v_mfma_f32_32x32x16_bf16 v[34:49], v[130:133], v[146:149], v[34:49]
	global_load_dwordx4 v[130:133], v[228:229], off offset:288
	v_mfma_f32_32x32x16_bf16 v[18:33], v[134:137], v[146:149], v[18:33]
	v_bitop3_b32 v134, v231, v234, 18 bitop3:0x36
	v_lshlrev_b32_e32 v134, 4, v134
	v_add3_u32 v163, 0, v134, v0
	ds_read_b128 v[134:137], v163
	v_add_u32_e32 v146, 0x14000, v167
	s_waitcnt vmcnt(0) lgkmcnt(0)
	v_mfma_f32_32x32x16_bf16 v[66:81], v[134:137], v[130:133], v[66:81]
	ds_read_b128 v[134:137], v163 offset:16384
	s_waitcnt lgkmcnt(0)
	v_mfma_f32_32x32x16_bf16 v[82:97], v[134:137], v[130:133], v[82:97]
	ds_read_b128 v[134:137], v163 offset:32768
	s_waitcnt lgkmcnt(0)
	v_mfma_f32_32x32x16_bf16 v[98:113], v[134:137], v[130:133], v[98:113]
	ds_read_b128 v[134:137], v163 offset:49152
	s_waitcnt lgkmcnt(0)
	v_mfma_f32_32x32x16_bf16 v[114:129], v[134:137], v[130:133], v[114:129]
	v_add_u32_e32 v134, 0x10000, v167
	ds_read_b128 v[134:137], v134
	s_waitcnt lgkmcnt(0)
	v_mfma_f32_32x32x16_bf16 v[2:17], v[134:137], v[142:145], v[2:17]
	ds_read_b128 v[134:137], v146
	global_load_dwordx4 v[146:149], v[228:229], off offset:320
	s_waitcnt lgkmcnt(0)
	v_mfma_f32_32x32x16_bf16 v[50:65], v[134:137], v[142:145], v[50:65]
	v_add_u32_e32 v134, 0x18000, v167
	ds_read_b128 v[134:137], v134
	s_waitcnt lgkmcnt(0)
	v_mfma_f32_32x32x16_bf16 v[34:49], v[134:137], v[142:145], v[34:49]
	v_add_u32_e32 v134, 0x1c000, v167
	ds_read_b128 v[134:137], v134
	s_waitcnt lgkmcnt(0)
	v_mfma_f32_32x32x16_bf16 v[18:33], v[134:137], v[142:145], v[18:33]
	v_bitop3_b32 v134, v231, v234, 20 bitop3:0x36
	v_lshlrev_b32_e32 v134, 4, v134
	v_add3_u32 v167, 0, v134, v0
	ds_read_b128 v[134:137], v167
	v_add_u32_e32 v142, 0x14000, v171
	s_waitcnt vmcnt(0) lgkmcnt(0)
	v_mfma_f32_32x32x16_bf16 v[66:81], v[134:137], v[146:149], v[66:81]
	ds_read_b128 v[134:137], v167 offset:16384
	s_waitcnt lgkmcnt(0)
	v_mfma_f32_32x32x16_bf16 v[82:97], v[134:137], v[146:149], v[82:97]
	ds_read_b128 v[134:137], v167 offset:32768
	s_waitcnt lgkmcnt(0)
	v_mfma_f32_32x32x16_bf16 v[98:113], v[134:137], v[146:149], v[98:113]
	ds_read_b128 v[134:137], v167 offset:49152
	s_waitcnt lgkmcnt(0)
	v_mfma_f32_32x32x16_bf16 v[114:129], v[134:137], v[146:149], v[114:129]
	v_add_u32_e32 v134, 0x10000, v171
	ds_read_b128 v[134:137], v134
	s_waitcnt lgkmcnt(0)
	v_mfma_f32_32x32x16_bf16 v[2:17], v[134:137], v[138:141], v[2:17]
	ds_read_b128 v[134:137], v142
	v_add_u32_e32 v142, 0x1c000, v171
	ds_read_b128 v[142:145], v142
	s_waitcnt lgkmcnt(1)
	v_mfma_f32_32x32x16_bf16 v[50:65], v[134:137], v[138:141], v[50:65]
	v_add_u32_e32 v134, 0x18000, v171
	ds_read_b128 v[134:137], v134
	s_waitcnt lgkmcnt(0)
	v_mfma_f32_32x32x16_bf16 v[34:49], v[134:137], v[138:141], v[34:49]
	global_load_dwordx4 v[134:137], v[228:229], off offset:352
	v_mfma_f32_32x32x16_bf16 v[18:33], v[142:145], v[138:141], v[18:33]
	v_bitop3_b32 v138, v231, v234, 22 bitop3:0x36
	v_lshlrev_b32_e32 v138, 4, v138
	v_add3_u32 v171, 0, v138, v0
	ds_read_b128 v[138:141], v171
	v_add_u32_e32 v142, 0x14000, v159
	s_waitcnt vmcnt(0) lgkmcnt(0)
	v_mfma_f32_32x32x16_bf16 v[66:81], v[138:141], v[134:137], v[66:81]
	ds_read_b128 v[138:141], v171 offset:16384
	s_waitcnt lgkmcnt(0)
	v_mfma_f32_32x32x16_bf16 v[82:97], v[138:141], v[134:137], v[82:97]
	ds_read_b128 v[138:141], v171 offset:32768
	s_waitcnt lgkmcnt(0)
	v_mfma_f32_32x32x16_bf16 v[98:113], v[138:141], v[134:137], v[98:113]
	ds_read_b128 v[138:141], v171 offset:49152
	s_waitcnt lgkmcnt(0)
	v_mfma_f32_32x32x16_bf16 v[114:129], v[138:141], v[134:137], v[114:129]
	v_add_u32_e32 v138, 0x10000, v159
	ds_read_b128 v[138:141], v138
	s_waitcnt lgkmcnt(0)
	v_mfma_f32_32x32x16_bf16 v[2:17], v[138:141], v[150:153], v[2:17]
	ds_read_b128 v[138:141], v142
	v_add_u32_e32 v142, 0x1c000, v159
	ds_read_b128 v[142:145], v142
	s_waitcnt lgkmcnt(1)
	v_mfma_f32_32x32x16_bf16 v[50:65], v[138:141], v[150:153], v[50:65]
	v_add_u32_e32 v138, 0x18000, v159
	ds_read_b128 v[138:141], v138
	s_waitcnt lgkmcnt(0)
	v_mfma_f32_32x32x16_bf16 v[34:49], v[138:141], v[150:153], v[34:49]
	global_load_dwordx4 v[138:141], v[228:229], off offset:384
	v_mfma_f32_32x32x16_bf16 v[18:33], v[142:145], v[150:153], v[18:33]
	v_bitop3_b32 v142, v231, v234, 24 bitop3:0x36
	v_lshlrev_b32_e32 v142, 4, v142
	v_add3_u32 v159, 0, v142, v0
	ds_read_b128 v[142:145], v159
	v_add_u32_e32 v150, 0x14000, v163
	s_waitcnt vmcnt(0) lgkmcnt(0)
	v_mfma_f32_32x32x16_bf16 v[66:81], v[142:145], v[138:141], v[66:81]
	ds_read_b128 v[142:145], v159 offset:16384
	s_waitcnt lgkmcnt(0)
	v_mfma_f32_32x32x16_bf16 v[82:97], v[142:145], v[138:141], v[82:97]
	ds_read_b128 v[142:145], v159 offset:32768
	s_waitcnt lgkmcnt(0)
	v_mfma_f32_32x32x16_bf16 v[98:113], v[142:145], v[138:141], v[98:113]
	ds_read_b128 v[142:145], v159 offset:49152
	s_waitcnt lgkmcnt(0)
	v_mfma_f32_32x32x16_bf16 v[114:129], v[142:145], v[138:141], v[114:129]
	v_add_u32_e32 v142, 0x10000, v163
	ds_read_b128 v[142:145], v142
	s_waitcnt lgkmcnt(0)
	v_mfma_f32_32x32x16_bf16 v[2:17], v[142:145], v[130:133], v[2:17]
	ds_read_b128 v[142:145], v150
	v_add_u32_e32 v150, 0x1c000, v163
	ds_read_b128 v[150:153], v150
	s_waitcnt lgkmcnt(1)
	v_mfma_f32_32x32x16_bf16 v[50:65], v[142:145], v[130:133], v[50:65]
	v_add_u32_e32 v142, 0x18000, v163
	ds_read_b128 v[142:145], v142
	s_waitcnt lgkmcnt(0)
	v_mfma_f32_32x32x16_bf16 v[34:49], v[142:145], v[130:133], v[34:49]
	global_load_dwordx4 v[142:145], v[228:229], off offset:416
	v_mfma_f32_32x32x16_bf16 v[18:33], v[150:153], v[130:133], v[18:33]
	v_bitop3_b32 v130, v231, v234, 26 bitop3:0x36
	v_lshlrev_b32_e32 v130, 4, v130
	v_add3_u32 v163, 0, v130, v0
	ds_read_b128 v[130:133], v163
	v_add_u32_e32 v150, 0x14000, v167
	s_waitcnt vmcnt(0) lgkmcnt(0)
	v_mfma_f32_32x32x16_bf16 v[66:81], v[130:133], v[142:145], v[66:81]
	v_add_u32_e32 v130, 0x10000, v167
	ds_read_b128 v[130:133], v130
	s_waitcnt lgkmcnt(0)
	v_mfma_f32_32x32x16_bf16 v[2:17], v[130:133], v[146:149], v[2:17]
	ds_read_b128 v[130:133], v150
	v_add_u32_e32 v150, 0x1c000, v167
	ds_read_b128 v[150:153], v150
	s_waitcnt lgkmcnt(1)
	v_mfma_f32_32x32x16_bf16 v[50:65], v[130:133], v[146:149], v[50:65]
	v_add_u32_e32 v130, 0x18000, v167
	ds_read_b128 v[130:133], v130
	s_waitcnt lgkmcnt(0)
	v_mfma_f32_32x32x16_bf16 v[34:49], v[130:133], v[146:149], v[34:49]
	global_load_dwordx4 v[130:133], v[228:229], off offset:448
	v_mfma_f32_32x32x16_bf16 v[18:33], v[150:153], v[146:149], v[18:33]
	global_load_dwordx4 v[146:149], v[228:229], off offset:480
	ds_read_b128 v[150:153], v163 offset:16384
	s_waitcnt lgkmcnt(0)
	v_mfma_f32_32x32x16_bf16 v[82:97], v[150:153], v[142:145], v[82:97]
	ds_read_b128 v[150:153], v163 offset:32768
	s_waitcnt lgkmcnt(0)
	v_mfma_f32_32x32x16_bf16 v[98:113], v[150:153], v[142:145], v[98:113]
	ds_read_b128 v[150:153], v163 offset:49152
	s_waitcnt lgkmcnt(0)
	v_mfma_f32_32x32x16_bf16 v[114:129], v[150:153], v[142:145], v[114:129]
	v_bitop3_b32 v150, v231, v234, 28 bitop3:0x36
	v_lshlrev_b32_e32 v150, 4, v150
	v_add3_u32 v167, 0, v150, v0
	ds_read_b128 v[150:153], v167
	s_waitcnt vmcnt(1) lgkmcnt(0)
	v_mfma_f32_32x32x16_bf16 v[66:81], v[150:153], v[130:133], v[66:81]
	ds_read_b128 v[150:153], v167 offset:16384
	s_waitcnt lgkmcnt(0)
	v_mfma_f32_32x32x16_bf16 v[82:97], v[150:153], v[130:133], v[82:97]
	ds_read_b128 v[150:153], v167 offset:32768
	s_waitcnt lgkmcnt(0)
	v_mfma_f32_32x32x16_bf16 v[98:113], v[150:153], v[130:133], v[98:113]
	ds_read_b128 v[150:153], v167 offset:49152
	s_waitcnt lgkmcnt(0)
	v_mfma_f32_32x32x16_bf16 v[114:129], v[150:153], v[130:133], v[114:129]
	v_bitop3_b32 v150, v231, v234, 30 bitop3:0x36
	v_lshlrev_b32_e32 v150, 4, v150
	v_add3_u32 v175, 0, v150, v0
	ds_read_b128 v[150:153], v175
	v_add_u32_e32 v0, 0x10000, v171
	s_waitcnt vmcnt(0) lgkmcnt(0)
	v_mfma_f32_32x32x16_bf16 v[66:81], v[150:153], v[146:149], v[66:81]
	ds_read_b128 v[150:153], v175 offset:16384
	s_waitcnt lgkmcnt(0)
	v_mfma_f32_32x32x16_bf16 v[82:97], v[150:153], v[146:149], v[82:97]
	ds_read_b128 v[150:153], v175 offset:32768
	s_waitcnt lgkmcnt(0)
	v_mfma_f32_32x32x16_bf16 v[98:113], v[150:153], v[146:149], v[98:113]
	ds_read_b128 v[150:153], v175 offset:49152
	s_waitcnt lgkmcnt(0)
	v_mfma_f32_32x32x16_bf16 v[114:129], v[150:153], v[146:149], v[114:129]
	ds_read_b128 v[150:153], v0
	v_add_u32_e32 v0, 0x14000, v171
	s_waitcnt lgkmcnt(0)
	v_mfma_f32_32x32x16_bf16 v[2:17], v[150:153], v[134:137], v[2:17]
	ds_read_b128 v[150:153], v0
	v_add_u32_e32 v0, 0x18000, v171
	s_waitcnt lgkmcnt(0)
	v_mfma_f32_32x32x16_bf16 v[50:65], v[150:153], v[134:137], v[50:65]
	ds_read_b128 v[150:153], v0
	v_add_u32_e32 v0, 0x1c000, v171
	s_waitcnt lgkmcnt(0)
	v_mfma_f32_32x32x16_bf16 v[34:49], v[150:153], v[134:137], v[34:49]
	ds_read_b128 v[150:153], v0
	v_add_u32_e32 v0, 0x10000, v159
	s_waitcnt lgkmcnt(0)
	v_mfma_f32_32x32x16_bf16 v[18:33], v[150:153], v[134:137], v[18:33]
	ds_read_b128 v[134:137], v0
	v_add_u32_e32 v0, 0x14000, v159
	s_waitcnt lgkmcnt(0)
	v_mfma_f32_32x32x16_bf16 v[2:17], v[134:137], v[138:141], v[2:17]
	ds_read_b128 v[134:137], v0
	v_add_u32_e32 v0, 0x18000, v159
	s_waitcnt lgkmcnt(0)
	v_mfma_f32_32x32x16_bf16 v[50:65], v[134:137], v[138:141], v[50:65]
	ds_read_b128 v[134:137], v0
	v_add_u32_e32 v0, 0x1c000, v159
	ds_read_b128 v[150:153], v0
	v_add_u32_e32 v0, 0x10000, v163
	s_waitcnt lgkmcnt(1)
	v_mfma_f32_32x32x16_bf16 v[34:49], v[134:137], v[138:141], v[34:49]
	v_lshlrev_b64 v[134:135], 6, v[226:227]
	v_lshl_add_u64 v[134:135], s[10:11], 0, v[134:135]
	v_lshl_add_u64 v[134:135], s[18:19], 2, v[134:135]
	global_load_dwordx4 v[134:137], v[134:135], off
	s_waitcnt lgkmcnt(0)
	v_mfma_f32_32x32x16_bf16 v[18:33], v[150:153], v[138:141], v[18:33]
	ds_read_b128 v[138:141], v0
	v_add_u32_e32 v0, 0x14000, v163
	s_waitcnt lgkmcnt(0)
	v_mfma_f32_32x32x16_bf16 v[2:17], v[138:141], v[142:145], v[2:17]
	ds_read_b128 v[138:141], v0
	v_add_u32_e32 v0, 0x18000, v163
	s_waitcnt lgkmcnt(0)
	v_mfma_f32_32x32x16_bf16 v[50:65], v[138:141], v[142:145], v[50:65]
	ds_read_b128 v[138:141], v0
	v_add_u32_e32 v0, 0x1c000, v163
	s_waitcnt lgkmcnt(0)
	v_mfma_f32_32x32x16_bf16 v[34:49], v[138:141], v[142:145], v[34:49]
	ds_read_b128 v[138:141], v0
	v_add_u32_e32 v0, 0x10000, v167
	s_waitcnt lgkmcnt(0)
	v_mfma_f32_32x32x16_bf16 v[18:33], v[138:141], v[142:145], v[18:33]
	ds_read_b128 v[138:141], v0
	v_add_u32_e32 v0, 0x14000, v167
	s_waitcnt vmcnt(0)
	v_mov_b32_e32 v142, v135
	s_waitcnt lgkmcnt(0)
	v_mfma_f32_32x32x16_bf16 v[2:17], v[138:141], v[130:133], v[2:17]
	ds_read_b128 v[138:141], v0
	v_add_u32_e32 v0, 0x18000, v167
	v_mov_b32_e32 v143, v136
	v_mov_b32_e32 v135, v137
	v_add_f32_e64 v142, v142, v134
	v_add_f32_e64 v143, v143, v135
	s_waitcnt lgkmcnt(0)
	v_mfma_f32_32x32x16_bf16 v[50:65], v[138:141], v[130:133], v[50:65]
	ds_read_b128 v[138:141], v0
	v_add_u32_e32 v0, 0x1c000, v167
	s_waitcnt lgkmcnt(0)
	v_mfma_f32_32x32x16_bf16 v[34:49], v[138:141], v[130:133], v[34:49]
	ds_read_b128 v[138:141], v0
	v_add_u32_e32 v0, 0x10000, v175
	ds_read_b128 v[134:137], v0
	v_add_f32_e32 v0, v142, v143
	v_fmamk_f32 v0, v0, 0x3b800000, v233
	v_cmp_gt_f32_e32 vcc, s82, v0
	s_waitcnt lgkmcnt(1)
	v_mfma_f32_32x32x16_bf16 v[18:33], v[138:141], v[130:133], v[18:33]
	v_mul_f32_e32 v130, 0x4b800000, v0
	v_cndmask_b32_e32 v0, v0, v130, vcc
	v_add_u32_e32 v130, 0x14000, v175
	ds_read_b128 v[138:141], v130
	v_rsq_f32_e32 v130, v0
	v_lshlrev_b32_e32 v0, 3, v231
	v_mul_f32_e32 v131, 0x45800000, v130
	v_cndmask_b32_e32 v130, v130, v131, vcc
	v_add_u32_e32 v131, 0x18000, v175
	s_waitcnt lgkmcnt(1)
	v_mfma_f32_32x32x16_bf16 v[2:17], v[134:137], v[146:149], v[2:17]
	ds_read_b128 v[132:135], v131
	v_add_u32_e32 v131, 0x1c000, v175
	s_waitcnt lgkmcnt(1)
	v_mfma_f32_32x32x16_bf16 v[50:65], v[138:141], v[146:149], v[50:65]
	ds_read_b128 v[136:139], v131
	v_lshlrev_b32_e32 v131, 2, v231
	v_and_b32_e32 v140, 3, v230
	s_waitcnt lgkmcnt(0)
	s_waitcnt lgkmcnt(0)
	s_barrier
	v_mfma_f32_32x32x16_bf16 v[34:49], v[132:135], v[146:149], v[34:49]
	v_bitop3_b32 v132, v131, v230, 28 bitop3:0x78
	v_or_b32_e32 v132, v132, v140
	v_lshlrev_b32_e32 v132, 4, v132
	v_mov_b32_e32 v133, v1
	v_lshl_add_u64 v[132:133], v[156:157], 0, v[132:133]
	v_lshl_add_u64 v[132:133], v[132:133], 0, s[48:49]
	s_mov_b32 s4, m0
	s_mov_b32 m0, s24
	s_nop 0
	global_load_lds_dwordx4 v[132:133], off
	s_mov_b32 m0, s4
	v_mfma_f32_32x32x16_bf16 v[18:33], v[136:139], v[146:149], v[18:33]
	v_lshlrev_b32_e32 v132, 2, v158
	v_xor_b32_e32 v132, v132, v230
	v_and_or_b32 v132, v132, 28, v140
	v_lshlrev_b32_e32 v132, 4, v132
	v_mov_b32_e32 v133, v1
	v_lshl_add_u64 v[132:133], v[160:161], 0, v[132:133]
	v_lshl_add_u64 v[132:133], v[132:133], 0, s[48:49]
	s_mov_b32 s4, m0
	s_mov_b32 m0, s25
	s_nop 0
	global_load_lds_dwordx4 v[132:133], off
	s_mov_b32 m0, s4
	v_lshlrev_b32_e32 v132, 2, v162
	v_xor_b32_e32 v132, v132, v230
	v_and_or_b32 v132, v132, 28, v140
	v_lshlrev_b32_e32 v132, 4, v132
	v_mov_b32_e32 v133, v1
	v_lshl_add_u64 v[132:133], v[164:165], 0, v[132:133]
	v_lshl_add_u64 v[132:133], v[132:133], 0, s[48:49]
	s_mov_b32 s4, m0
	s_mov_b32 m0, s26
	s_nop 0
	global_load_lds_dwordx4 v[132:133], off
	s_mov_b32 m0, s4
	v_lshlrev_b32_e32 v132, 2, v166
	v_xor_b32_e32 v132, v132, v230
	v_and_or_b32 v132, v132, 28, v140
	v_lshlrev_b32_e32 v132, 4, v132
	v_mov_b32_e32 v133, v1
	v_lshl_add_u64 v[132:133], v[168:169], 0, v[132:133]
	v_lshl_add_u64 v[132:133], v[132:133], 0, s[48:49]
	s_mov_b32 s4, m0
	s_mov_b32 m0, s27
	s_nop 0
	global_load_lds_dwordx4 v[132:133], off
	s_mov_b32 m0, s4
	v_lshlrev_b32_e32 v132, 2, v170
	v_xor_b32_e32 v132, v132, v230
	v_and_or_b32 v132, v132, 28, v140
	v_lshlrev_b32_e32 v132, 4, v132
	v_mov_b32_e32 v133, v1
	v_lshl_add_u64 v[132:133], v[172:173], 0, v[132:133]
	v_lshl_add_u64 v[132:133], v[132:133], 0, s[48:49]
	s_mov_b32 s4, m0
	s_mov_b32 m0, s28
	s_nop 0
	global_load_lds_dwordx4 v[132:133], off
	s_mov_b32 m0, s4
	v_lshlrev_b32_e32 v132, 2, v174
	v_xor_b32_e32 v132, v132, v230
	v_and_or_b32 v132, v132, 28, v140
	v_lshlrev_b32_e32 v132, 4, v132
	v_mov_b32_e32 v133, v1
	v_lshl_add_u64 v[132:133], v[176:177], 0, v[132:133]
	v_lshl_add_u64 v[132:133], v[132:133], 0, s[48:49]
	s_mov_b32 s4, m0
	s_mov_b32 m0, s29
	s_nop 0
	global_load_lds_dwordx4 v[132:133], off
	s_mov_b32 m0, s4
	v_lshlrev_b32_e32 v132, 2, v178
	v_xor_b32_e32 v132, v132, v230
	v_and_or_b32 v132, v132, 28, v140
	v_lshlrev_b32_e32 v132, 4, v132
	v_mov_b32_e32 v133, v1
	v_lshl_add_u64 v[132:133], v[180:181], 0, v[132:133]
	v_lshl_add_u64 v[132:133], v[132:133], 0, s[48:49]
	s_mov_b32 s4, m0
	s_mov_b32 m0, s30
	s_nop 0
	global_load_lds_dwordx4 v[132:133], off
	s_mov_b32 m0, s4
	v_lshlrev_b32_e32 v132, 2, v182
	v_xor_b32_e32 v132, v132, v230
	v_and_or_b32 v132, v132, 28, v140
	v_lshlrev_b32_e32 v132, 4, v132
	v_mov_b32_e32 v133, v1
	v_lshl_add_u64 v[132:133], v[184:185], 0, v[132:133]
	v_lshl_add_u64 v[132:133], v[132:133], 0, s[48:49]
	s_mov_b32 s4, m0
	s_mov_b32 m0, s31
	s_nop 0
	global_load_lds_dwordx4 v[132:133], off
	s_mov_b32 m0, s4
	v_lshlrev_b32_e32 v132, 2, v186
	v_xor_b32_e32 v132, v132, v230
	v_and_or_b32 v132, v132, 28, v140
	v_lshlrev_b32_e32 v132, 4, v132
	v_mov_b32_e32 v133, v1
	v_lshl_add_u64 v[132:133], v[188:189], 0, v[132:133]
	v_lshl_add_u64 v[132:133], v[132:133], 0, s[48:49]
	s_mov_b32 s4, m0
	s_mov_b32 m0, s34
	s_nop 0
	global_load_lds_dwordx4 v[132:133], off
	s_mov_b32 m0, s4
	v_lshlrev_b32_e32 v132, 2, v190
	v_xor_b32_e32 v132, v132, v230
	v_and_or_b32 v132, v132, 28, v140
	v_lshlrev_b32_e32 v132, 4, v132
	v_mov_b32_e32 v133, v1
	v_lshl_add_u64 v[132:133], v[192:193], 0, v[132:133]
	v_lshl_add_u64 v[132:133], v[132:133], 0, s[48:49]
	s_mov_b32 s4, m0
	s_mov_b32 m0, s35
	s_nop 0
	global_load_lds_dwordx4 v[132:133], off
	s_mov_b32 m0, s4
	v_lshlrev_b32_e32 v132, 2, v202
	v_xor_b32_e32 v132, v132, v230
	v_and_or_b32 v132, v132, 28, v140
	v_lshlrev_b32_e32 v132, 4, v132
	v_mov_b32_e32 v133, v1
	v_lshl_add_u64 v[132:133], v[204:205], 0, v[132:133]
	v_lshl_add_u64 v[132:133], v[132:133], 0, s[48:49]
	s_mov_b32 s4, m0
	s_mov_b32 m0, s36
	s_nop 0
	global_load_lds_dwordx4 v[132:133], off
	s_mov_b32 m0, s4
	v_lshlrev_b32_e32 v132, 2, v206
	v_xor_b32_e32 v132, v132, v230
	v_and_or_b32 v132, v132, 28, v140
	v_lshlrev_b32_e32 v132, 4, v132
	v_mov_b32_e32 v133, v1
	v_lshl_add_u64 v[132:133], v[208:209], 0, v[132:133]
	v_lshl_add_u64 v[132:133], v[132:133], 0, s[48:49]
	s_mov_b32 s4, m0
	s_mov_b32 m0, s37
	s_nop 0
	global_load_lds_dwordx4 v[132:133], off
	s_mov_b32 m0, s4
	v_lshlrev_b32_e32 v132, 2, v210
	v_xor_b32_e32 v132, v132, v230
	v_and_or_b32 v132, v132, 28, v140
	v_lshlrev_b32_e32 v132, 4, v132
	v_mov_b32_e32 v133, v1
	v_lshl_add_u64 v[132:133], v[212:213], 0, v[132:133]
	v_lshl_add_u64 v[132:133], v[132:133], 0, s[48:49]
	s_mov_b32 s4, m0
	s_mov_b32 m0, s38
	s_nop 0
	global_load_lds_dwordx4 v[132:133], off
	s_mov_b32 m0, s4
	v_lshlrev_b32_e32 v132, 2, v214
	v_xor_b32_e32 v132, v132, v230
	v_and_or_b32 v132, v132, 28, v140
	v_lshlrev_b32_e32 v132, 4, v132
	v_mov_b32_e32 v133, v1
	v_lshl_add_u64 v[132:133], v[216:217], 0, v[132:133]
	v_lshl_add_u64 v[132:133], v[132:133], 0, s[48:49]
	s_mov_b32 s4, m0
	s_mov_b32 m0, s39
	s_nop 0
	global_load_lds_dwordx4 v[132:133], off
	s_mov_b32 m0, s4
	v_lshlrev_b32_e32 v132, 2, v218
	v_xor_b32_e32 v132, v132, v230
	v_and_or_b32 v132, v132, 28, v140
	v_lshlrev_b32_e32 v132, 4, v132
	v_mov_b32_e32 v133, v1
	v_lshl_add_u64 v[132:133], v[220:221], 0, v[132:133]
	v_lshl_add_u64 v[132:133], v[132:133], 0, s[48:49]
	s_mov_b32 s4, m0
	s_mov_b32 m0, s40
	s_nop 0
	global_load_lds_dwordx4 v[132:133], off
	s_mov_b32 m0, s4
	v_lshlrev_b32_e32 v132, 2, v222
	v_xor_b32_e32 v132, v132, v230
	v_and_or_b32 v132, v132, 28, v140
	v_lshlrev_b32_e32 v132, 4, v132
	v_mov_b32_e32 v133, v1
	v_lshl_add_u64 v[132:133], v[224:225], 0, v[132:133]
	v_lshl_add_u64 v[132:133], v[132:133], 0, s[48:49]
	s_mov_b32 s4, m0
	s_mov_b32 m0, s20
	s_nop 0
	global_load_lds_dwordx4 v[132:133], off
	s_mov_b32 m0, s4
	v_mul_f32_e32 v82, v130, v82
	v_exp_f32_e32 v133, v82
	v_mul_f32_e32 v82, v130, v83
	v_exp_f32_e32 v134, v82
	v_mul_f32_e32 v82, v130, v84
	v_exp_f32_e32 v135, v82
	v_mul_f32_e32 v82, v130, v85
	v_exp_f32_e32 v136, v82
	v_mul_f32_e32 v82, v130, v86
	v_exp_f32_e32 v137, v82
	v_mul_f32_e32 v82, v130, v87
	v_exp_f32_e32 v138, v82
	v_mul_f32_e32 v82, v130, v88
	v_exp_f32_e32 v139, v82
	v_mul_f32_e32 v82, v130, v89
	v_exp_f32_e32 v89, v82
	v_mul_f32_e32 v82, v130, v90
	v_exp_f32_e32 v140, v82
	v_mul_f32_e32 v82, v130, v91
	v_exp_f32_e32 v141, v82
	v_mul_f32_e32 v82, v130, v92
	v_exp_f32_e32 v142, v82
	v_mul_f32_e32 v82, v130, v93
	v_exp_f32_e32 v143, v82
	v_mul_f32_e32 v82, v130, v94
	v_exp_f32_e32 v144, v82
	v_mul_f32_e32 v82, v130, v95
	v_mul_f32_e32 v81, v130, v81
	v_mul_f32_e32 v66, v130, v66
	v_exp_f32_e32 v145, v82
	v_mul_f32_e32 v82, v130, v96
	v_exp_f32_e32 v147, v81
	v_exp_f32_e32 v81, v66
	v_mul_f32_e32 v66, v130, v67
	v_exp_f32_e32 v146, v82
	v_exp_f32_e32 v82, v66
	v_mul_f32_e32 v66, v130, v68
	v_exp_f32_e32 v83, v66
	v_mul_f32_e32 v66, v130, v69
	v_exp_f32_e32 v84, v66
	v_mul_f32_e32 v66, v130, v70
	v_exp_f32_e32 v85, v66
	v_mul_f32_e32 v66, v130, v71
	v_add_f32_e32 v90, 0, v81
	v_exp_f32_e32 v86, v66
	v_mul_f32_e32 v66, v130, v72
	v_add_f32_e32 v90, v82, v90
	v_exp_f32_e32 v87, v66
	v_mul_f32_e32 v66, v130, v73
	v_add_f32_e32 v90, v83, v90
	v_exp_f32_e32 v88, v66
	v_mul_f32_e32 v66, v130, v74
	v_add_f32_e32 v90, v84, v90
	v_exp_f32_e32 v74, v66
	v_mul_f32_e32 v66, v130, v75
	v_add_f32_e32 v90, v85, v90
	v_exp_f32_e32 v75, v66
	v_mul_f32_e32 v66, v130, v76
	v_add_f32_e32 v90, v86, v90
	v_exp_f32_e32 v76, v66
	v_mul_f32_e32 v66, v130, v77
	v_add_f32_e32 v90, v87, v90
	v_exp_f32_e32 v77, v66
	v_mul_f32_e32 v66, v130, v78
	v_add_f32_e32 v90, v88, v90
	v_exp_f32_e32 v78, v66
	v_mul_f32_e32 v66, v130, v79
	v_add_f32_e32 v90, v74, v90
	v_exp_f32_e32 v79, v66
	v_mul_f32_e32 v66, v130, v80
	v_add_f32_e32 v90, v75, v90
	v_exp_f32_e32 v80, v66
	v_add_f32_e32 v90, v76, v90
	v_add_f32_e32 v90, v77, v90
	v_add_f32_e32 v90, v78, v90
	v_add_f32_e32 v90, v79, v90
	v_add_f32_e32 v90, v80, v90
	v_add_f32_e32 v90, v147, v90
	v_add_f32_e32 v90, v133, v90
	v_add_f32_e32 v90, v134, v90
	v_add_f32_e32 v90, v135, v90
	v_add_f32_e32 v90, v136, v90
	v_add_f32_e32 v90, v137, v90
	v_add_f32_e32 v90, v138, v90
	v_add_f32_e32 v90, v139, v90
	v_add_f32_e32 v90, v89, v90
	v_add_f32_e32 v90, v140, v90
	v_add_f32_e32 v90, v141, v90
	v_mul_f32_e32 v97, v130, v97
	v_add_f32_e32 v90, v142, v90
	v_mul_f32_e32 v98, v130, v98
	v_exp_f32_e32 v132, v97
	v_add_f32_e32 v90, v143, v90
	v_exp_f32_e32 v98, v98
	v_mul_f32_e32 v99, v130, v99
	v_add_f32_e32 v90, v144, v90
	v_exp_f32_e32 v99, v99
	v_mul_f32_e32 v100, v130, v100
	v_add_f32_e32 v90, v145, v90
	v_exp_f32_e32 v100, v100
	v_mul_f32_e32 v101, v130, v101
	v_add_f32_e32 v90, v146, v90
	v_exp_f32_e32 v101, v101
	v_mul_f32_e32 v102, v130, v102
	v_add_f32_e32 v90, v132, v90
	v_exp_f32_e32 v102, v102
	v_mul_f32_e32 v103, v130, v103
	v_add_f32_e32 v90, v98, v90
	v_exp_f32_e32 v103, v103
	v_mul_f32_e32 v104, v130, v104
	v_add_f32_e32 v90, v99, v90
	v_exp_f32_e32 v104, v104
	v_mul_f32_e32 v105, v130, v105
	v_add_f32_e32 v90, v100, v90
	v_exp_f32_e32 v105, v105
	v_mul_f32_e32 v106, v130, v106
	v_add_f32_e32 v90, v101, v90
	v_exp_f32_e32 v106, v106
	v_mul_f32_e32 v107, v130, v107
	v_add_f32_e32 v90, v102, v90
	v_exp_f32_e32 v107, v107
	v_mul_f32_e32 v108, v130, v108
	v_add_f32_e32 v90, v103, v90
	v_exp_f32_e32 v108, v108
	v_mul_f32_e32 v109, v130, v109
	v_add_f32_e32 v90, v104, v90
	v_exp_f32_e32 v109, v109
	v_mul_f32_e32 v110, v130, v110
	v_add_f32_e32 v90, v105, v90
	v_exp_f32_e32 v110, v110
	v_mul_f32_e32 v111, v130, v111
	v_add_f32_e32 v90, v106, v90
	v_exp_f32_e32 v111, v111
	v_mul_f32_e32 v112, v130, v112
	v_add_f32_e32 v90, v107, v90
	v_mul_f32_e32 v113, v130, v113
	v_exp_f32_e32 v112, v112
	v_add_f32_e32 v90, v108, v90
	v_mul_f32_e32 v114, v130, v114
	v_exp_f32_e32 v113, v113
	v_add_f32_e32 v90, v109, v90
	v_exp_f32_e32 v114, v114
	v_mul_f32_e32 v115, v130, v115
	v_add_f32_e32 v90, v110, v90
	v_exp_f32_e32 v115, v115
	v_mul_f32_e32 v116, v130, v116
	v_add_f32_e32 v90, v111, v90
	v_exp_f32_e32 v116, v116
	v_mul_f32_e32 v117, v130, v117
	v_add_f32_e32 v90, v112, v90
	v_exp_f32_e32 v117, v117
	v_mul_f32_e32 v118, v130, v118
	v_add_f32_e32 v90, v113, v90
	v_exp_f32_e32 v118, v118
	v_mul_f32_e32 v119, v130, v119
	v_add_f32_e32 v90, v114, v90
	v_exp_f32_e32 v119, v119
	v_mul_f32_e32 v120, v130, v120
	v_add_f32_e32 v90, v115, v90
	v_exp_f32_e32 v120, v120
	v_mul_f32_e32 v121, v130, v121
	v_add_f32_e32 v90, v116, v90
	v_exp_f32_e32 v121, v121
	v_mul_f32_e32 v122, v130, v122
	v_add_f32_e32 v90, v117, v90
	v_exp_f32_e32 v122, v122
	v_mul_f32_e32 v123, v130, v123
	v_add_f32_e32 v90, v118, v90
	v_exp_f32_e32 v123, v123
	v_mul_f32_e32 v124, v130, v124
	v_add_f32_e32 v90, v119, v90
	v_exp_f32_e32 v124, v124
	v_mul_f32_e32 v125, v130, v125
	v_add_f32_e32 v90, v120, v90
	v_exp_f32_e32 v125, v125
	v_mul_f32_e32 v126, v130, v126
	v_add_f32_e32 v90, v121, v90
	v_exp_f32_e32 v126, v126
	v_mul_f32_e32 v127, v130, v127
	v_add_f32_e32 v90, v122, v90
	v_exp_f32_e32 v127, v127
	v_mul_f32_e32 v128, v130, v128
	v_add_f32_e32 v90, v123, v90
	v_mul_f32_e32 v129, v130, v129
	v_exp_f32_e32 v128, v128
	v_add_f32_e32 v90, v124, v90
	v_exp_f32_e32 v129, v129
	v_add_f32_e32 v90, v125, v90
	v_mul_f32_e32 v2, v130, v2
	v_add_f32_e32 v90, v126, v90
	v_exp_f32_e32 v2, v2
	v_mul_f32_e32 v3, v130, v3
	v_add_f32_e32 v90, v127, v90
	v_exp_f32_e32 v3, v3
	v_mul_f32_e32 v4, v130, v4
	v_add_f32_e32 v90, v128, v90
	v_exp_f32_e32 v4, v4
	v_mul_f32_e32 v5, v130, v5
	v_add_f32_e32 v148, v129, v90
	v_exp_f32_e32 v5, v5
	v_mul_f32_e32 v6, v130, v6
	v_cvt_pk_bf16_f32 v66, v122, v123
	v_cvt_pk_bf16_f32 v122, v74, v75
	v_add_f32_e32 v74, v148, v2
	v_exp_f32_e32 v6, v6
	v_mul_f32_e32 v7, v130, v7
	v_add_f32_e32 v74, v3, v74
	v_exp_f32_e32 v7, v7
	v_mul_f32_e32 v8, v130, v8
	v_add_f32_e32 v74, v4, v74
	v_exp_f32_e32 v8, v8
	v_mul_f32_e32 v9, v130, v9
	v_add_f32_e32 v74, v5, v74
	v_exp_f32_e32 v9, v9
	v_mul_f32_e32 v10, v130, v10
	v_add_f32_e32 v74, v6, v74
	v_exp_f32_e32 v10, v10
	v_mul_f32_e32 v11, v130, v11
	v_add_f32_e32 v74, v7, v74
	v_exp_f32_e32 v11, v11
	v_mul_f32_e32 v12, v130, v12
	v_add_f32_e32 v74, v8, v74
	v_exp_f32_e32 v12, v12
	v_mul_f32_e32 v13, v130, v13
	v_add_f32_e32 v74, v9, v74
	v_exp_f32_e32 v13, v13
	v_mul_f32_e32 v14, v130, v14
	v_add_f32_e32 v74, v10, v74
	v_exp_f32_e32 v14, v14
	v_mul_f32_e32 v15, v130, v15
	v_add_f32_e32 v74, v11, v74
	v_exp_f32_e32 v15, v15
	v_mul_f32_e32 v16, v130, v16
	v_add_f32_e32 v74, v12, v74
	v_exp_f32_e32 v16, v16
	v_mul_f32_e32 v17, v130, v17
	v_cvt_pk_bf16_f32 v92, v110, v111
	v_add_f32_e32 v74, v13, v74
	v_exp_f32_e32 v17, v17
	v_cvt_pk_bf16_f32 v110, v2, v3
	v_mul_f32_e32 v2, v130, v50
	v_add_f32_e32 v74, v14, v74
	v_cvt_pk_bf16_f32 v111, v4, v5
	v_exp_f32_e32 v2, v2
	v_mul_f32_e32 v4, v130, v51
	v_add_f32_e32 v74, v15, v74
	v_exp_f32_e32 v4, v4
	v_mul_f32_e32 v5, v130, v52
	v_cvt_pk_bf16_f32 v93, v112, v113
	v_add_f32_e32 v74, v16, v74
	v_cvt_pk_bf16_f32 v112, v6, v7
	v_exp_f32_e32 v5, v5
	v_mul_f32_e32 v6, v130, v53
	v_add_f32_e32 v74, v17, v74
	v_exp_f32_e32 v6, v6
	v_mul_f32_e32 v7, v130, v54
	v_cvt_pk_bf16_f32 v113, v8, v9
	v_add_f32_e32 v3, v2, v74
	v_exp_f32_e32 v7, v7
	v_mul_f32_e32 v8, v130, v55
	v_add_f32_e32 v3, v4, v3
	v_exp_f32_e32 v8, v8
	v_mul_f32_e32 v9, v130, v56
	v_cvt_pk_bf16_f32 v90, v106, v107
	v_cvt_pk_bf16_f32 v106, v10, v11
	v_add_f32_e32 v3, v5, v3
	v_exp_f32_e32 v9, v9
	v_mul_f32_e32 v10, v130, v57
	v_add_f32_e32 v3, v6, v3
	v_exp_f32_e32 v10, v10
	v_mul_f32_e32 v11, v130, v58
	v_cvt_pk_bf16_f32 v107, v12, v13
	v_add_f32_e32 v3, v7, v3
	v_exp_f32_e32 v11, v11
	v_mul_f32_e32 v12, v130, v59
	v_add_f32_e32 v3, v8, v3
	v_exp_f32_e32 v12, v12
	v_mul_f32_e32 v13, v130, v60
	v_cvt_pk_bf16_f32 v91, v108, v109
	v_cvt_pk_bf16_f32 v108, v14, v15
	v_add_f32_e32 v3, v9, v3
	v_exp_f32_e32 v13, v13
	v_mul_f32_e32 v14, v130, v61
	v_add_f32_e32 v3, v10, v3
	v_exp_f32_e32 v14, v14
	v_mul_f32_e32 v15, v130, v62
	v_cvt_pk_bf16_f32 v109, v16, v17
	v_add_f32_e32 v3, v11, v3
	v_exp_f32_e32 v15, v15
	v_mul_f32_e32 v16, v130, v63
	v_add_f32_e32 v3, v12, v3
	v_exp_f32_e32 v16, v16
	v_mul_f32_e32 v17, v130, v64
	v_add_f32_e32 v3, v13, v3
	v_exp_f32_e32 v17, v17
	v_mul_f32_e32 v50, v130, v65
	v_cvt_pk_bf16_f32 v96, v102, v103
	v_add_f32_e32 v3, v14, v3
	v_exp_f32_e32 v50, v50
	v_cvt_pk_bf16_f32 v102, v2, v4
	v_mul_f32_e32 v2, v130, v34
	v_add_f32_e32 v3, v15, v3
	v_exp_f32_e32 v2, v2
	v_mul_f32_e32 v4, v130, v35
	v_add_f32_e32 v3, v16, v3
	v_cvt_pk_bf16_f32 v103, v5, v6
	v_exp_f32_e32 v4, v4
	v_mul_f32_e32 v5, v130, v36
	v_add_f32_e32 v3, v17, v3
	v_exp_f32_e32 v5, v5
	v_mul_f32_e32 v6, v130, v37
	v_cvt_pk_bf16_f32 v97, v104, v105
	v_add_f32_e32 v3, v50, v3
	v_cvt_pk_bf16_f32 v104, v7, v8
	v_exp_f32_e32 v6, v6
	v_mul_f32_e32 v7, v130, v38
	v_add_f32_e32 v3, v2, v3
	v_exp_f32_e32 v7, v7
	v_mul_f32_e32 v8, v130, v39
	v_cvt_pk_bf16_f32 v105, v9, v10
	v_add_f32_e32 v3, v4, v3
	v_exp_f32_e32 v8, v8
	v_mul_f32_e32 v9, v130, v40
	v_add_f32_e32 v3, v5, v3
	v_exp_f32_e32 v9, v9
	v_mul_f32_e32 v10, v130, v41
	v_cvt_pk_bf16_f32 v94, v98, v99
	v_cvt_pk_bf16_f32 v98, v11, v12
	v_add_f32_e32 v3, v6, v3
	v_exp_f32_e32 v10, v10
	v_mul_f32_e32 v11, v130, v42
	v_add_f32_e32 v3, v7, v3
	v_exp_f32_e32 v11, v11
	v_mul_f32_e32 v12, v130, v43
	v_cvt_pk_bf16_f32 v99, v13, v14
	v_add_f32_e32 v3, v8, v3
	v_exp_f32_e32 v12, v12
	v_mul_f32_e32 v13, v130, v44
	v_add_f32_e32 v3, v9, v3
	v_exp_f32_e32 v13, v13
	v_mul_f32_e32 v14, v130, v45
	v_cvt_pk_bf16_f32 v95, v100, v101
	v_cvt_pk_bf16_f32 v100, v15, v16
	v_add_f32_e32 v3, v10, v3
	v_exp_f32_e32 v14, v14
	v_mul_f32_e32 v15, v130, v46
	v_add_f32_e32 v3, v11, v3
	v_exp_f32_e32 v15, v15
	v_mul_f32_e32 v16, v130, v47
	v_cvt_pk_bf16_f32 v101, v17, v50
	v_add_f32_e32 v3, v12, v3
	v_exp_f32_e32 v16, v16
	v_mul_f32_e32 v17, v130, v48
	v_add_f32_e32 v3, v13, v3
	v_exp_f32_e32 v17, v17
	v_mul_f32_e32 v34, v130, v49
	v_cvt_pk_bf16_f32 v69, v128, v129
	v_cvt_pk_bf16_f32 v128, v85, v86
	v_add_f32_e32 v3, v14, v3
	v_exp_f32_e32 v34, v34
	v_cvt_pk_bf16_f32 v86, v2, v4
	v_mul_f32_e32 v2, v130, v18
	v_add_f32_e32 v3, v15, v3
	v_exp_f32_e32 v2, v2
	v_mul_f32_e32 v4, v130, v19
	v_cvt_pk_bf16_f32 v129, v87, v88
	v_add_f32_e32 v3, v16, v3
	v_cvt_pk_bf16_f32 v87, v5, v6
	v_exp_f32_e32 v4, v4
	v_mul_f32_e32 v5, v130, v20
	v_add_f32_e32 v3, v17, v3
	v_exp_f32_e32 v5, v5
	v_mul_f32_e32 v6, v130, v21
	v_add_f32_e32 v3, v34, v3
	v_cvt_pk_bf16_f32 v88, v7, v8
	v_exp_f32_e32 v6, v6
	v_mul_f32_e32 v7, v130, v22
	v_add_f32_e32 v3, v2, v3
	v_exp_f32_e32 v7, v7
	v_mul_f32_e32 v8, v130, v23
	v_cvt_pk_bf16_f32 v73, v120, v121
	v_cvt_pk_bf16_f32 v121, v139, v89
	v_cvt_pk_bf16_f32 v89, v9, v10
	v_add_f32_e32 v3, v4, v3
	v_exp_f32_e32 v8, v8
	v_mul_f32_e32 v9, v130, v24
	v_add_f32_e32 v3, v5, v3
	v_exp_f32_e32 v9, v9
	v_mul_f32_e32 v10, v130, v25
	v_cvt_pk_bf16_f32 v68, v126, v127
	v_cvt_pk_bf16_f32 v126, v81, v82
	v_cvt_pk_bf16_f32 v82, v11, v12
	v_add_f32_e32 v3, v6, v3
	v_exp_f32_e32 v10, v10
	v_mul_f32_e32 v11, v130, v26
	v_add_f32_e32 v3, v7, v3
	v_exp_f32_e32 v11, v11
	v_mul_f32_e32 v12, v130, v27
	v_cvt_pk_bf16_f32 v127, v83, v84
	v_cvt_pk_bf16_f32 v83, v13, v14
	v_add_f32_e32 v3, v8, v3
	v_exp_f32_e32 v12, v12
	v_mul_f32_e32 v13, v130, v28
	v_add_f32_e32 v3, v9, v3
	v_exp_f32_e32 v13, v13
	v_mul_f32_e32 v14, v130, v29
	v_cvt_pk_bf16_f32 v84, v15, v16
	v_add_f32_e32 v3, v10, v3
	v_exp_f32_e32 v14, v14
	v_mul_f32_e32 v15, v130, v30
	v_add_f32_e32 v3, v11, v3
	v_exp_f32_e32 v15, v15
	v_mul_f32_e32 v16, v130, v31
	v_cvt_pk_bf16_f32 v85, v17, v34
	v_add_f32_e32 v3, v12, v3
	v_exp_f32_e32 v16, v16
	v_mul_f32_e32 v17, v130, v32
	v_add_f32_e32 v3, v13, v3
	v_exp_f32_e32 v17, v17
	v_mul_f32_e32 v18, v130, v33
	v_cvt_pk_bf16_f32 v67, v124, v125
	v_cvt_pk_bf16_f32 v124, v78, v79
	v_add_f32_e32 v3, v14, v3
	v_exp_f32_e32 v18, v18
	v_cvt_pk_bf16_f32 v78, v2, v4
	v_and_b32_e32 v4, 64, v238
	v_add_f32_e32 v3, v15, v3
	v_xor_b32_e32 v2, 32, v238
	v_add_u32_e32 v4, 64, v4
	v_add_f32_e32 v3, v16, v3
	v_cmp_lt_i32_e32 vcc, v2, v4
	v_add_f32_e32 v3, v17, v3
	v_add_f32_e32 v3, v18, v3
	v_cndmask_b32_e32 v2, v238, v2, vcc
	v_lshlrev_b32_e32 v2, 2, v2
	ds_bpermute_b32 v2, v2, v3
	v_cvt_pk_bf16_f32 v79, v5, v6
	v_cvt_pk_bf16_f32 v125, v80, v147
	v_cvt_pk_bf16_f32 v80, v7, v8
	v_cvt_pk_bf16_f32 v71, v116, v117
	s_waitcnt lgkmcnt(0)
	v_add_f32_e32 v2, v3, v2
	v_div_scale_f32 v3, s[18:19], v2, v2, 1.0
	v_rcp_f32_e32 v4, v3
	v_cvt_pk_bf16_f32 v72, v118, v119
	v_cvt_pk_bf16_f32 v117, v146, v132
	v_cvt_pk_bf16_f32 v118, v133, v134
	v_fma_f32 v5, -v3, v4, 1.0
	v_fmac_f32_e32 v4, v5, v4
	v_div_scale_f32 v5, vcc, 1.0, v2, 1.0
	v_mul_f32_e32 v6, v5, v4
	v_fma_f32 v7, -v3, v6, v5
	v_fmac_f32_e32 v6, v7, v4
	v_fma_f32 v3, -v3, v6, v5
	v_div_fmas_f32 v3, v3, v4, v6
	v_div_fixup_f32 v130, v3, v2, 1.0
	v_lshl_add_u64 v[2:3], s[12:13], 0, v[154:155]
	v_lshl_add_u64 v[2:3], v[2:3], 0, s[16:17]
	v_lshrrev_b32_e32 v4, 2, v230
	v_lshl_add_u64 v[2:3], v[2:3], 0, v[0:1]
	v_lshlrev_b32_e32 v5, 1, v230
	v_lshlrev_b32_e32 v6, 3, v230
	v_lshl_add_u64 v[132:133], v[2:3], 0, v[0:1]
	v_and_or_b32 v0, v4, 3, v131
	v_and_b32_e32 v5, 32, v5
	v_and_b32_e32 v6, 24, v6
	v_lshl_add_u32 v2, v0, 9, 0
	v_add3_u32 v148, v2, v5, v6
	v_lshlrev_b32_e32 v149, 6, v0
	v_add_u32_e32 v0, v148, v149
	s_waitcnt vmcnt(0)
	s_barrier
	ds_read_b64_tr_b16 v[2:3], v0
	ds_read_b64_tr_b16 v[4:5], v0 offset:4096
	v_xor_b32_e32 v166, 64, v149
	v_add_u32_e32 v131, v148, v166
	v_cvt_pk_bf16_f32 v123, v76, v77
	v_cvt_pk_bf16_f32 v81, v9, v10
	v_cvt_pk_bf16_f32 v74, v11, v12
	v_cvt_pk_bf16_f32 v75, v13, v14
	v_cvt_pk_bf16_f32 v77, v17, v18
	ds_read_b64_tr_b16 v[6:7], v131
	ds_read_b64_tr_b16 v[8:9], v131 offset:4096
	ds_read_b64_tr_b16 v[10:11], v0 offset:8192
	ds_read_b64_tr_b16 v[12:13], v0 offset:12288
	ds_read_b64_tr_b16 v[18:19], v131 offset:8192
	ds_read_b64_tr_b16 v[20:21], v131 offset:12288
	s_waitcnt lgkmcnt(6)
	v_mfma_f32_32x32x16_bf16 v[34:49], v[2:5], v[126:129], 0
	v_cvt_pk_bf16_f32 v76, v15, v16
	v_cvt_pk_bf16_f32 v70, v114, v115
	v_cvt_pk_bf16_f32 v114, v140, v141
	v_cvt_pk_bf16_f32 v115, v142, v143
	v_cvt_pk_bf16_f32 v116, v144, v145
	v_cvt_pk_bf16_f32 v119, v135, v136
	v_cvt_pk_bf16_f32 v120, v137, v138
	s_waitcnt lgkmcnt(2)
	v_mfma_f32_32x32x16_bf16 v[50:65], v[10:13], v[122:125], 0
	ds_read_b64_tr_b16 v[134:135], v0 offset:16384
	ds_read_b64_tr_b16 v[136:137], v0 offset:20480
	ds_read_b64_tr_b16 v[138:139], v131 offset:16384
	ds_read_b64_tr_b16 v[140:141], v131 offset:20480
	ds_read_b64_tr_b16 v[142:143], v0 offset:24576
	ds_read_b64_tr_b16 v[144:145], v0 offset:28672
	ds_read_b64_tr_b16 v[150:151], v131 offset:24576
	ds_read_b64_tr_b16 v[152:153], v131 offset:28672
	v_add_u32_e32 v147, 0x10000, v148
	v_add_u32_e32 v146, 0x11000, v148
	v_xor_b32_e32 v168, 0xc0, v149
	v_add_u32_e32 v169, v148, v168
	s_add_u32 s14, s14, s46
	s_addc_u32 s15, s15, s47
	v_mfma_f32_32x32x16_bf16 v[2:17], v[6:9], v[126:129], 0
	s_mov_b64 s[16:17], 0
	s_waitcnt lgkmcnt(8)
	v_mfma_f32_32x32x16_bf16 v[18:33], v[18:21], v[122:125], 0
	s_waitcnt lgkmcnt(6)
	v_mfma_f32_32x32x16_bf16 v[34:49], v[134:137], v[118:121], v[34:49]
	s_waitcnt lgkmcnt(2)
	v_mfma_f32_32x32x16_bf16 v[50:65], v[142:145], v[114:117], v[50:65]
	v_mfma_f32_32x32x16_bf16 v[2:17], v[138:141], v[118:121], v[2:17]
	s_waitcnt lgkmcnt(0)
	v_mfma_f32_32x32x16_bf16 v[18:33], v[150:153], v[114:117], v[18:33]
	ds_read_b64_tr_b16 v[134:135], v0 offset:32768
	ds_read_b64_tr_b16 v[136:137], v0 offset:36864
	ds_read_b64_tr_b16 v[138:139], v131 offset:32768
	ds_read_b64_tr_b16 v[140:141], v131 offset:36864
	ds_read_b64_tr_b16 v[142:143], v0 offset:40960
	ds_read_b64_tr_b16 v[144:145], v0 offset:45056
	ds_read_b64_tr_b16 v[150:151], v131 offset:40960
	ds_read_b64_tr_b16 v[152:153], v131 offset:45056
	s_waitcnt lgkmcnt(6)
	v_mfma_f32_32x32x16_bf16 v[34:49], v[134:137], v[94:97], v[34:49]
	s_waitcnt lgkmcnt(2)
	v_mfma_f32_32x32x16_bf16 v[50:65], v[142:145], v[90:93], v[50:65]
	v_mfma_f32_32x32x16_bf16 v[2:17], v[138:141], v[94:97], v[2:17]
	s_waitcnt lgkmcnt(0)
	v_mfma_f32_32x32x16_bf16 v[18:33], v[150:153], v[90:93], v[18:33]
	ds_read_b64_tr_b16 v[134:135], v0 offset:49152
	ds_read_b64_tr_b16 v[136:137], v0 offset:53248
	ds_read_b64_tr_b16 v[138:139], v131 offset:49152
	ds_read_b64_tr_b16 v[140:141], v131 offset:53248
	ds_read_b64_tr_b16 v[142:143], v0 offset:57344
	ds_read_b64_tr_b16 v[144:145], v0 offset:61440
	ds_read_b64_tr_b16 v[150:151], v131 offset:57344
	ds_read_b64_tr_b16 v[152:153], v131 offset:61440
	v_add_u32_e32 v0, v147, v149
	v_add_u32_e32 v131, 0x1e000, v148
	s_waitcnt lgkmcnt(6)
	v_mfma_f32_32x32x16_bf16 v[34:49], v[134:137], v[70:73], v[34:49]
	ds_read_b64_tr_b16 v[134:135], v0
	v_add_u32_e32 v0, v146, v149
	ds_read_b64_tr_b16 v[136:137], v0
	v_add_u32_e32 v0, v147, v166
	s_waitcnt lgkmcnt(4)
	v_mfma_f32_32x32x16_bf16 v[50:65], v[142:145], v[66:69], v[50:65]
	v_add_u32_e32 v145, 0x12000, v148
	v_add_u32_e32 v144, 0x13000, v148
	v_add_u32_e32 v143, 0x14000, v148
	v_add_u32_e32 v142, 0x15000, v148
	v_mfma_f32_32x32x16_bf16 v[2:17], v[138:141], v[70:73], v[2:17]
	ds_read_b64_tr_b16 v[138:139], v0
	v_add_u32_e32 v0, v146, v166
	ds_read_b64_tr_b16 v[140:141], v0
	v_add_u32_e32 v0, v145, v149
	s_waitcnt lgkmcnt(4)
	v_mfma_f32_32x32x16_bf16 v[18:33], v[150:153], v[66:69], v[18:33]
	ds_read_b64_tr_b16 v[150:151], v0
	v_add_u32_e32 v0, v144, v149
	ds_read_b64_tr_b16 v[152:153], v0
	v_add_u32_e32 v0, v145, v166
	ds_read_b64_tr_b16 v[154:155], v0
	v_add_u32_e32 v0, v144, v166
	ds_read_b64_tr_b16 v[156:157], v0
	v_add_u32_e32 v0, v143, v149
	s_waitcnt lgkmcnt(6)
	v_mfma_f32_32x32x16_bf16 v[34:49], v[134:137], v[110:113], v[34:49]
	ds_read_b64_tr_b16 v[134:135], v0
	v_add_u32_e32 v0, v142, v149
	ds_read_b64_tr_b16 v[136:137], v0
	v_add_u32_e32 v0, v143, v166
	s_waitcnt lgkmcnt(4)
	v_mfma_f32_32x32x16_bf16 v[50:65], v[150:153], v[106:109], v[50:65]
	ds_read_b64_tr_b16 v[150:151], v0
	v_add_u32_e32 v0, v142, v166
	ds_read_b64_tr_b16 v[152:153], v0
	v_mfma_f32_32x32x16_bf16 v[2:17], v[138:141], v[110:113], v[2:17]
	v_add_u32_e32 v141, 0x16000, v148
	v_add_u32_e32 v140, 0x17000, v148
	v_add_u32_e32 v0, v141, v149
	v_add_u32_e32 v139, 0x18000, v148
	v_add_u32_e32 v138, 0x19000, v148
	s_waitcnt lgkmcnt(4)
	v_mfma_f32_32x32x16_bf16 v[18:33], v[154:157], v[106:109], v[18:33]
	ds_read_b64_tr_b16 v[154:155], v0
	v_add_u32_e32 v0, v140, v149
	ds_read_b64_tr_b16 v[156:157], v0
	v_add_u32_e32 v0, v141, v166
	ds_read_b64_tr_b16 v[158:159], v0
	v_add_u32_e32 v0, v140, v166
	ds_read_b64_tr_b16 v[160:161], v0
	v_add_u32_e32 v0, v139, v149
	s_waitcnt lgkmcnt(4)
	v_mfma_f32_32x32x16_bf16 v[2:17], v[150:153], v[102:105], v[2:17]
	ds_read_b64_tr_b16 v[150:151], v0
	v_add_u32_e32 v0, v138, v149
	ds_read_b64_tr_b16 v[152:153], v0
	v_add_u32_e32 v0, v139, v166
	v_mfma_f32_32x32x16_bf16 v[34:49], v[134:137], v[102:105], v[34:49]
	v_add_u32_e32 v137, 0x1a000, v148
	v_add_u32_e32 v136, 0x1b000, v148
	v_add_u32_e32 v135, 0x1c000, v148
	v_add_u32_e32 v134, 0x1d000, v148
	s_waitcnt lgkmcnt(4)
	v_mfma_f32_32x32x16_bf16 v[50:65], v[154:157], v[98:101], v[50:65]
	ds_read_b64_tr_b16 v[154:155], v0
	v_add_u32_e32 v0, v138, v166
	ds_read_b64_tr_b16 v[156:157], v0
	v_add_u32_e32 v0, v137, v149
	s_waitcnt lgkmcnt(4)
	v_mfma_f32_32x32x16_bf16 v[18:33], v[158:161], v[98:101], v[18:33]
	ds_read_b64_tr_b16 v[158:159], v0
	v_add_u32_e32 v0, v136, v149
	ds_read_b64_tr_b16 v[160:161], v0
	v_add_u32_e32 v0, v137, v166
	ds_read_b64_tr_b16 v[162:163], v0
	s_waitcnt lgkmcnt(1)
	v_mfma_f32_32x32x16_bf16 v[50:65], v[158:161], v[82:85], v[50:65]
	v_add_u32_e32 v158, v131, v149
	ds_read_b64_tr_b16 v[158:159], v158
	v_add_u32_e32 v0, v136, v166
	ds_read_b64_tr_b16 v[164:165], v0
	v_add_u32_e32 v0, v135, v149
	s_waitcnt lgkmcnt(0)
	v_mfma_f32_32x32x16_bf16 v[18:33], v[162:165], v[82:85], v[18:33]
	v_add_u32_e32 v162, v131, v166
	ds_read_b64_tr_b16 v[162:163], v162
	v_mfma_f32_32x32x16_bf16 v[34:49], v[150:153], v[86:89], v[34:49]
	ds_read_b64_tr_b16 v[150:151], v0
	v_add_u32_e32 v0, v134, v149
	ds_read_b64_tr_b16 v[152:153], v0
	v_add_u32_e32 v0, v135, v166
	v_mfma_f32_32x32x16_bf16 v[2:17], v[154:157], v[86:89], v[2:17]
	ds_read_b64_tr_b16 v[154:155], v0
	v_add_u32_e32 v0, v134, v166
	ds_read_b64_tr_b16 v[156:157], v0
	v_add_u32_e32 v0, 0x1f000, v148
	v_add_u32_e32 v160, v0, v149
	v_add_u32_e32 v164, v0, v166
	ds_read_b64_tr_b16 v[160:161], v160
	ds_read_b64_tr_b16 v[164:165], v164
	s_waitcnt lgkmcnt(4)
	v_mfma_f32_32x32x16_bf16 v[34:49], v[150:153], v[78:81], v[34:49]
	v_xor_b32_e32 v166, 0x80, v149
	v_add_u32_e32 v167, v148, v166
	s_waitcnt lgkmcnt(1)
	v_mfma_f32_32x32x16_bf16 v[50:65], v[158:161], v[74:77], v[50:65]
	v_mfma_f32_32x32x16_bf16 v[2:17], v[154:157], v[78:81], v[2:17]
	s_nop 10
	v_add_f32_e64 v36, v36, v52
	v_add_f32_e64 v37, v37, v53
	v_add_f32_e64 v34, v34, v50
	v_add_f32_e64 v35, v35, v51
	v_add_f32_e64 v40, v40, v56
	v_add_f32_e64 v41, v41, v57
	v_add_f32_e32 v38, v38, v54
	v_add_f32_e32 v39, v39, v55
	v_mul_f32_e32 v34, v130, v34
	v_mul_f32_e32 v35, v130, v35
	v_mul_f32_e32 v36, v130, v36
	v_mul_f32_e32 v37, v130, v37
	v_cvt_pk_bf16_f32 v34, v34, v35
	s_waitcnt lgkmcnt(0)
	v_mfma_f32_32x32x16_bf16 v[18:33], v[162:165], v[74:77], v[18:33]
	v_cvt_pk_bf16_f32 v35, v36, v37
	v_mul_f32_e64 v36, v130, v38
	v_mul_f32_e64 v37, v130, v39
	v_mul_f32_e64 v38, v130, v40
	v_mul_f32_e64 v39, v130, v41
	v_cvt_pk_bf16_f32 v36, v36, v37
	v_cvt_pk_bf16_f32 v37, v38, v39
	v_add_f32_e32 v44, v44, v60
	v_add_f32_e32 v45, v45, v61
	v_add_f32_e32 v42, v42, v58
	v_add_f32_e32 v43, v43, v59
	s_nop 2
	v_add_f32_e32 v4, v4, v20
	v_add_f32_e32 v5, v5, v21
	v_add_f32_e32 v2, v2, v18
	v_add_f32_e32 v3, v3, v19
	v_add_f32_e32 v8, v8, v24
	v_add_f32_e32 v9, v9, v25
	v_add_f32_e32 v6, v6, v22
	v_add_f32_e32 v7, v7, v23
	v_mul_f32_e32 v2, v130, v2
	v_mul_f32_e32 v3, v130, v3
	v_mul_f32_e32 v4, v130, v4
	v_mul_f32_e32 v5, v130, v5
	v_cvt_pk_bf16_f32 v2, v2, v3
	v_cvt_pk_bf16_f32 v3, v4, v5
	v_mul_f32_e32 v4, v130, v6
	v_mul_f32_e32 v5, v130, v7
	v_mul_f32_e32 v6, v130, v8
	v_mul_f32_e32 v7, v130, v9
	v_cvt_pk_bf16_f32 v4, v4, v5
	v_cvt_pk_bf16_f32 v5, v6, v7
	v_permlane32_swap_b32_e32 v34, v36
	v_permlane32_swap_b32_e32 v35, v37
	v_add_f32_e32 v12, v12, v28
	v_add_f32_e32 v13, v13, v29
	v_add_f32_e32 v10, v10, v26
	v_add_f32_e32 v11, v11, v27
	v_permlane32_swap_b32_e32 v2, v4
	v_permlane32_swap_b32_e32 v3, v5
	v_add_f32_e32 v48, v48, v64
	v_add_f32_e32 v49, v49, v65
	v_add_f32_e32 v46, v46, v62
	v_add_f32_e32 v47, v47, v63
	global_store_dwordx4 v[132:133], v[34:37], off
	v_add_f32_e32 v16, v16, v32
	v_add_f32_e32 v17, v17, v33
	v_add_f32_e32 v14, v14, v30
	v_add_f32_e32 v15, v15, v31
	v_mul_f32_e32 v34, v130, v42
	v_mul_f32_e32 v35, v130, v43
	v_mul_f32_e32 v36, v130, v44
	v_mul_f32_e32 v37, v130, v45
	global_store_dwordx4 v[132:133], v[2:5], off offset:64
	v_cvt_pk_bf16_f32 v34, v34, v35
	v_cvt_pk_bf16_f32 v35, v36, v37
	v_mul_f32_e32 v2, v130, v10
	v_mul_f32_e32 v3, v130, v11
	v_mul_f32_e32 v4, v130, v12
	v_mul_f32_e32 v5, v130, v13
	v_mul_f32_e32 v36, v130, v46
	v_mul_f32_e32 v37, v130, v47
	v_mul_f32_e32 v38, v130, v48
	v_mul_f32_e32 v39, v130, v49
	v_cvt_pk_bf16_f32 v2, v2, v3
	v_cvt_pk_bf16_f32 v3, v4, v5
	v_mul_f32_e32 v4, v130, v14
	v_mul_f32_e32 v5, v130, v15
	v_mul_f32_e32 v6, v130, v16
	v_mul_f32_e32 v7, v130, v17
	v_cvt_pk_bf16_f32 v36, v36, v37
	v_cvt_pk_bf16_f32 v37, v38, v39
	v_cvt_pk_bf16_f32 v4, v4, v5
	v_cvt_pk_bf16_f32 v5, v6, v7
	v_permlane32_swap_b32_e32 v34, v36
	v_permlane32_swap_b32_e32 v35, v37
	v_permlane32_swap_b32_e32 v2, v4
	v_permlane32_swap_b32_e32 v3, v5
	global_store_dwordx4 v[132:133], v[34:37], off offset:32
	global_store_dwordx4 v[132:133], v[2:5], off offset:96
	ds_read_b64_tr_b16 v[2:3], v167
	ds_read_b64_tr_b16 v[4:5], v167 offset:4096
	ds_read_b64_tr_b16 v[6:7], v169
	ds_read_b64_tr_b16 v[8:9], v169 offset:4096
	ds_read_b64_tr_b16 v[10:11], v167 offset:8192
	ds_read_b64_tr_b16 v[12:13], v167 offset:12288
	ds_read_b64_tr_b16 v[18:19], v169 offset:8192
	ds_read_b64_tr_b16 v[20:21], v169 offset:12288
	s_waitcnt lgkmcnt(6)
	v_mfma_f32_32x32x16_bf16 v[34:49], v[2:5], v[126:129], 0
	ds_read_b64_tr_b16 v[150:151], v167 offset:16384
	ds_read_b64_tr_b16 v[152:153], v167 offset:20480
	ds_read_b64_tr_b16 v[154:155], v169 offset:16384
	ds_read_b64_tr_b16 v[156:157], v169 offset:20480
	ds_read_b64_tr_b16 v[158:159], v167 offset:24576
	ds_read_b64_tr_b16 v[160:161], v167 offset:28672
	ds_read_b64_tr_b16 v[162:163], v169 offset:24576
	ds_read_b64_tr_b16 v[164:165], v169 offset:28672
	s_waitcnt lgkmcnt(10)
	v_mfma_f32_32x32x16_bf16 v[50:65], v[10:13], v[122:125], 0
	v_mfma_f32_32x32x16_bf16 v[2:17], v[6:9], v[126:129], 0
	s_waitcnt lgkmcnt(8)
	v_mfma_f32_32x32x16_bf16 v[18:33], v[18:21], v[122:125], 0
	s_waitcnt lgkmcnt(6)
	v_mfma_f32_32x32x16_bf16 v[34:49], v[150:153], v[118:121], v[34:49]
	s_waitcnt lgkmcnt(2)
	v_mfma_f32_32x32x16_bf16 v[50:65], v[158:161], v[114:117], v[50:65]
	v_mfma_f32_32x32x16_bf16 v[2:17], v[154:157], v[118:121], v[2:17]
	s_waitcnt lgkmcnt(0)
	v_mfma_f32_32x32x16_bf16 v[18:33], v[162:165], v[114:117], v[18:33]
	ds_read_b64_tr_b16 v[150:151], v167 offset:32768
	ds_read_b64_tr_b16 v[152:153], v167 offset:36864
	ds_read_b64_tr_b16 v[154:155], v169 offset:32768
	ds_read_b64_tr_b16 v[156:157], v169 offset:36864
	ds_read_b64_tr_b16 v[158:159], v167 offset:40960
	ds_read_b64_tr_b16 v[160:161], v167 offset:45056
	ds_read_b64_tr_b16 v[162:163], v169 offset:40960
	ds_read_b64_tr_b16 v[164:165], v169 offset:45056
	s_waitcnt lgkmcnt(6)
	v_mfma_f32_32x32x16_bf16 v[34:49], v[150:153], v[94:97], v[34:49]
	s_waitcnt lgkmcnt(2)
	v_mfma_f32_32x32x16_bf16 v[50:65], v[158:161], v[90:93], v[50:65]
	v_mfma_f32_32x32x16_bf16 v[2:17], v[154:157], v[94:97], v[2:17]
	s_waitcnt lgkmcnt(0)
	v_mfma_f32_32x32x16_bf16 v[18:33], v[162:165], v[90:93], v[18:33]
	ds_read_b64_tr_b16 v[150:151], v167 offset:49152
	ds_read_b64_tr_b16 v[152:153], v167 offset:53248
	ds_read_b64_tr_b16 v[154:155], v169 offset:49152
	ds_read_b64_tr_b16 v[156:157], v169 offset:53248
	ds_read_b64_tr_b16 v[158:159], v167 offset:57344
	ds_read_b64_tr_b16 v[160:161], v167 offset:61440
	ds_read_b64_tr_b16 v[162:163], v169 offset:57344
	ds_read_b64_tr_b16 v[164:165], v169 offset:61440
	s_waitcnt lgkmcnt(6)
	v_mfma_f32_32x32x16_bf16 v[34:49], v[150:153], v[70:73], v[34:49]
	v_add_u32_e32 v150, v147, v166
	v_add_u32_e32 v152, v146, v166
	ds_read_b64_tr_b16 v[150:151], v150
	ds_read_b64_tr_b16 v[152:153], v152
	s_waitcnt lgkmcnt(4)
	v_mfma_f32_32x32x16_bf16 v[50:65], v[158:161], v[66:69], v[50:65]
	v_add_u32_e32 v158, v145, v166
	v_add_u32_e32 v160, v144, v166
	ds_read_b64_tr_b16 v[158:159], v158
	ds_read_b64_tr_b16 v[160:161], v160
	v_mfma_f32_32x32x16_bf16 v[2:17], v[154:157], v[70:73], v[2:17]
	v_add_u32_e32 v154, v147, v168
	v_add_u32_e32 v156, v146, v168
	ds_read_b64_tr_b16 v[154:155], v154
	ds_read_b64_tr_b16 v[156:157], v156
	s_waitcnt lgkmcnt(6)
	v_mfma_f32_32x32x16_bf16 v[18:33], v[162:165], v[66:69], v[18:33]
	v_add_u32_e32 v162, v145, v168
	v_add_u32_e32 v164, v144, v168
	ds_read_b64_tr_b16 v[162:163], v162
	ds_read_b64_tr_b16 v[164:165], v164
	s_waitcnt lgkmcnt(6)
	v_mfma_f32_32x32x16_bf16 v[34:49], v[150:153], v[110:113], v[34:49]
	v_add_u32_e32 v150, v143, v166
	v_add_u32_e32 v152, v142, v166
	ds_read_b64_tr_b16 v[150:151], v150
	ds_read_b64_tr_b16 v[152:153], v152
	s_waitcnt lgkmcnt(6)
	v_mfma_f32_32x32x16_bf16 v[50:65], v[158:161], v[106:109], v[50:65]
	v_add_u32_e32 v158, v141, v166
	v_add_u32_e32 v160, v140, v166
	ds_read_b64_tr_b16 v[158:159], v158
	ds_read_b64_tr_b16 v[160:161], v160
	s_waitcnt lgkmcnt(6)
	v_mfma_f32_32x32x16_bf16 v[2:17], v[154:157], v[110:113], v[2:17]
	v_add_u32_e32 v154, v143, v168
	v_add_u32_e32 v156, v142, v168
	ds_read_b64_tr_b16 v[154:155], v154
	ds_read_b64_tr_b16 v[156:157], v156
	s_waitcnt lgkmcnt(6)
	v_mfma_f32_32x32x16_bf16 v[18:33], v[162:165], v[106:109], v[18:33]
	v_add_u32_e32 v162, v141, v168
	v_add_u32_e32 v164, v140, v168
	ds_read_b64_tr_b16 v[162:163], v162
	ds_read_b64_tr_b16 v[164:165], v164
	s_waitcnt lgkmcnt(6)
	v_mfma_f32_32x32x16_bf16 v[34:49], v[150:153], v[102:105], v[34:49]
	v_add_u32_e32 v150, v139, v166
	v_add_u32_e32 v152, v138, v166
	ds_read_b64_tr_b16 v[150:151], v150
	ds_read_b64_tr_b16 v[152:153], v152
	s_waitcnt lgkmcnt(6)
	v_mfma_f32_32x32x16_bf16 v[50:65], v[158:161], v[98:101], v[50:65]
	v_add_u32_e32 v158, v137, v166
	v_add_u32_e32 v160, v136, v166
	ds_read_b64_tr_b16 v[158:159], v158
	ds_read_b64_tr_b16 v[160:161], v160
	s_waitcnt lgkmcnt(6)
	v_mfma_f32_32x32x16_bf16 v[2:17], v[154:157], v[102:105], v[2:17]
	v_add_u32_e32 v154, v139, v168
	v_add_u32_e32 v156, v138, v168
	ds_read_b64_tr_b16 v[154:155], v154
	ds_read_b64_tr_b16 v[156:157], v156
	s_waitcnt lgkmcnt(6)
	v_mfma_f32_32x32x16_bf16 v[18:33], v[162:165], v[98:101], v[18:33]
	v_add_u32_e32 v162, v137, v168
	v_add_u32_e32 v164, v136, v168
	ds_read_b64_tr_b16 v[162:163], v162
	ds_read_b64_tr_b16 v[164:165], v164
	s_waitcnt lgkmcnt(6)
	v_mfma_f32_32x32x16_bf16 v[34:49], v[150:153], v[86:89], v[34:49]
	v_add_u32_e32 v150, v135, v166
	v_add_u32_e32 v152, v134, v166
	ds_read_b64_tr_b16 v[150:151], v150
	ds_read_b64_tr_b16 v[152:153], v152
	s_waitcnt lgkmcnt(6)
	v_mfma_f32_32x32x16_bf16 v[50:65], v[158:161], v[82:85], v[50:65]
	v_add_u32_e32 v158, v131, v166
	v_add_u32_e32 v160, v0, v166
	ds_read_b64_tr_b16 v[158:159], v158
	ds_read_b64_tr_b16 v[160:161], v160
	v_xor_b32_e32 v166, 0x100, v149
	v_add_u32_e32 v167, v148, v166
	s_waitcnt lgkmcnt(6)
	v_mfma_f32_32x32x16_bf16 v[2:17], v[154:157], v[86:89], v[2:17]
	v_add_u32_e32 v154, v135, v168
	v_add_u32_e32 v156, v134, v168
	ds_read_b64_tr_b16 v[154:155], v154
	ds_read_b64_tr_b16 v[156:157], v156
	s_waitcnt lgkmcnt(6)
	v_mfma_f32_32x32x16_bf16 v[18:33], v[162:165], v[82:85], v[18:33]
	v_add_u32_e32 v162, v131, v168
	v_add_u32_e32 v164, v0, v168
	ds_read_b64_tr_b16 v[162:163], v162
	ds_read_b64_tr_b16 v[164:165], v164
	v_xor_b32_e32 v168, 0x140, v149
	v_add_u32_e32 v169, v148, v168
	s_waitcnt lgkmcnt(6)
	v_mfma_f32_32x32x16_bf16 v[34:49], v[150:153], v[78:81], v[34:49]
	s_waitcnt lgkmcnt(4)
	v_mfma_f32_32x32x16_bf16 v[50:65], v[158:161], v[74:77], v[50:65]
	s_waitcnt lgkmcnt(2)
	v_mfma_f32_32x32x16_bf16 v[2:17], v[154:157], v[78:81], v[2:17]
	s_nop 9
	v_add_f32_e64 v36, v36, v52
	v_add_f32_e64 v37, v37, v53
	v_add_f32_e64 v34, v34, v50
	v_add_f32_e64 v35, v35, v51
	v_add_f32_e64 v40, v40, v56
	v_add_f32_e64 v41, v41, v57
	v_add_f32_e32 v38, v38, v54
	v_add_f32_e32 v39, v39, v55
	v_mul_f32_e32 v34, v130, v34
	v_mul_f32_e32 v35, v130, v35
	v_mul_f32_e32 v36, v130, v36
	v_mul_f32_e32 v37, v130, v37
	v_cvt_pk_bf16_f32 v34, v34, v35
	s_waitcnt lgkmcnt(0)
	v_mfma_f32_32x32x16_bf16 v[18:33], v[162:165], v[74:77], v[18:33]
	v_cvt_pk_bf16_f32 v35, v36, v37
	v_mul_f32_e64 v36, v130, v38
	v_mul_f32_e64 v37, v130, v39
	v_mul_f32_e64 v38, v130, v40
	v_mul_f32_e64 v39, v130, v41
	v_cvt_pk_bf16_f32 v36, v36, v37
	v_cvt_pk_bf16_f32 v37, v38, v39
	v_add_f32_e32 v44, v44, v60
	v_add_f32_e32 v45, v45, v61
	v_add_f32_e32 v42, v42, v58
	v_add_f32_e32 v43, v43, v59
	s_nop 2
	v_add_f32_e32 v4, v4, v20
	v_add_f32_e32 v5, v5, v21
	v_add_f32_e32 v2, v2, v18
	v_add_f32_e32 v3, v3, v19
	v_add_f32_e32 v8, v8, v24
	v_add_f32_e32 v9, v9, v25
	v_add_f32_e32 v6, v6, v22
	v_add_f32_e32 v7, v7, v23
	v_mul_f32_e32 v2, v130, v2
	v_mul_f32_e32 v3, v130, v3
	v_mul_f32_e32 v4, v130, v4
	v_mul_f32_e32 v5, v130, v5
	v_cvt_pk_bf16_f32 v2, v2, v3
	v_cvt_pk_bf16_f32 v3, v4, v5
	v_mul_f32_e32 v4, v130, v6
	v_mul_f32_e32 v5, v130, v7
	v_mul_f32_e32 v6, v130, v8
	v_mul_f32_e32 v7, v130, v9
	v_cvt_pk_bf16_f32 v4, v4, v5
	v_cvt_pk_bf16_f32 v5, v6, v7
	v_permlane32_swap_b32_e32 v34, v36
	v_permlane32_swap_b32_e32 v35, v37
	v_add_f32_e32 v12, v12, v28
	v_add_f32_e32 v13, v13, v29
	v_add_f32_e32 v10, v10, v26
	v_add_f32_e32 v11, v11, v27
	v_permlane32_swap_b32_e32 v2, v4
	v_permlane32_swap_b32_e32 v3, v5
	v_add_f32_e32 v48, v48, v64
	v_add_f32_e32 v49, v49, v65
	v_add_f32_e32 v46, v46, v62
	v_add_f32_e32 v47, v47, v63
	global_store_dwordx4 v[132:133], v[34:37], off offset:128
	v_add_f32_e32 v16, v16, v32
	v_add_f32_e32 v17, v17, v33
	v_add_f32_e32 v14, v14, v30
	v_add_f32_e32 v15, v15, v31
	v_mul_f32_e32 v34, v130, v42
	v_mul_f32_e32 v35, v130, v43
	v_mul_f32_e32 v36, v130, v44
	v_mul_f32_e32 v37, v130, v45
	global_store_dwordx4 v[132:133], v[2:5], off offset:192
	v_cvt_pk_bf16_f32 v34, v34, v35
	v_cvt_pk_bf16_f32 v35, v36, v37
	v_mul_f32_e32 v2, v130, v10
	v_mul_f32_e32 v3, v130, v11
	v_mul_f32_e32 v4, v130, v12
	v_mul_f32_e32 v5, v130, v13
	v_mul_f32_e32 v36, v130, v46
	v_mul_f32_e32 v37, v130, v47
	v_mul_f32_e32 v38, v130, v48
	v_mul_f32_e32 v39, v130, v49
	v_cvt_pk_bf16_f32 v2, v2, v3
	v_cvt_pk_bf16_f32 v3, v4, v5
	v_mul_f32_e32 v4, v130, v14
	v_mul_f32_e32 v5, v130, v15
	v_mul_f32_e32 v6, v130, v16
	v_mul_f32_e32 v7, v130, v17
	v_cvt_pk_bf16_f32 v36, v36, v37
	v_cvt_pk_bf16_f32 v37, v38, v39
	v_cvt_pk_bf16_f32 v4, v4, v5
	v_cvt_pk_bf16_f32 v5, v6, v7
	v_permlane32_swap_b32_e32 v34, v36
	v_permlane32_swap_b32_e32 v35, v37
	v_permlane32_swap_b32_e32 v2, v4
	v_permlane32_swap_b32_e32 v3, v5
	global_store_dwordx4 v[132:133], v[34:37], off offset:160
	global_store_dwordx4 v[132:133], v[2:5], off offset:224
	ds_read_b64_tr_b16 v[2:3], v167
	ds_read_b64_tr_b16 v[4:5], v167 offset:4096
	ds_read_b64_tr_b16 v[6:7], v169
	ds_read_b64_tr_b16 v[8:9], v169 offset:4096
	ds_read_b64_tr_b16 v[10:11], v167 offset:8192
	ds_read_b64_tr_b16 v[12:13], v167 offset:12288
	ds_read_b64_tr_b16 v[18:19], v169 offset:8192
	ds_read_b64_tr_b16 v[20:21], v169 offset:12288
	s_waitcnt lgkmcnt(6)
	v_mfma_f32_32x32x16_bf16 v[34:49], v[2:5], v[126:129], 0
	ds_read_b64_tr_b16 v[150:151], v167 offset:16384
	ds_read_b64_tr_b16 v[152:153], v167 offset:20480
	ds_read_b64_tr_b16 v[154:155], v169 offset:16384
	ds_read_b64_tr_b16 v[156:157], v169 offset:20480
	ds_read_b64_tr_b16 v[158:159], v167 offset:24576
	ds_read_b64_tr_b16 v[160:161], v167 offset:28672
	ds_read_b64_tr_b16 v[162:163], v169 offset:24576
	ds_read_b64_tr_b16 v[164:165], v169 offset:28672
	s_waitcnt lgkmcnt(10)
	v_mfma_f32_32x32x16_bf16 v[50:65], v[10:13], v[122:125], 0
	v_mfma_f32_32x32x16_bf16 v[2:17], v[6:9], v[126:129], 0
	s_waitcnt lgkmcnt(8)
	v_mfma_f32_32x32x16_bf16 v[18:33], v[18:21], v[122:125], 0
	s_waitcnt lgkmcnt(6)
	v_mfma_f32_32x32x16_bf16 v[34:49], v[150:153], v[118:121], v[34:49]
	s_waitcnt lgkmcnt(2)
	v_mfma_f32_32x32x16_bf16 v[50:65], v[158:161], v[114:117], v[50:65]
	v_mfma_f32_32x32x16_bf16 v[2:17], v[154:157], v[118:121], v[2:17]
	s_waitcnt lgkmcnt(0)
	v_mfma_f32_32x32x16_bf16 v[18:33], v[162:165], v[114:117], v[18:33]
	ds_read_b64_tr_b16 v[150:151], v167 offset:32768
	ds_read_b64_tr_b16 v[152:153], v167 offset:36864
	ds_read_b64_tr_b16 v[154:155], v169 offset:32768
	ds_read_b64_tr_b16 v[156:157], v169 offset:36864
	ds_read_b64_tr_b16 v[158:159], v167 offset:40960
	ds_read_b64_tr_b16 v[160:161], v167 offset:45056
	ds_read_b64_tr_b16 v[162:163], v169 offset:40960
	ds_read_b64_tr_b16 v[164:165], v169 offset:45056
	s_waitcnt lgkmcnt(6)
	v_mfma_f32_32x32x16_bf16 v[34:49], v[150:153], v[94:97], v[34:49]
	s_waitcnt lgkmcnt(2)
	v_mfma_f32_32x32x16_bf16 v[50:65], v[158:161], v[90:93], v[50:65]
	v_mfma_f32_32x32x16_bf16 v[2:17], v[154:157], v[94:97], v[2:17]
	s_waitcnt lgkmcnt(0)
	v_mfma_f32_32x32x16_bf16 v[18:33], v[162:165], v[90:93], v[18:33]
	ds_read_b64_tr_b16 v[150:151], v167 offset:49152
	ds_read_b64_tr_b16 v[152:153], v167 offset:53248
	ds_read_b64_tr_b16 v[154:155], v169 offset:49152
	ds_read_b64_tr_b16 v[156:157], v169 offset:53248
	ds_read_b64_tr_b16 v[158:159], v167 offset:57344
	ds_read_b64_tr_b16 v[160:161], v167 offset:61440
	ds_read_b64_tr_b16 v[162:163], v169 offset:57344
	ds_read_b64_tr_b16 v[164:165], v169 offset:61440
	s_waitcnt lgkmcnt(6)
	v_mfma_f32_32x32x16_bf16 v[34:49], v[150:153], v[70:73], v[34:49]
	v_add_u32_e32 v150, v147, v166
	v_add_u32_e32 v152, v146, v166
	ds_read_b64_tr_b16 v[150:151], v150
	ds_read_b64_tr_b16 v[152:153], v152
	s_waitcnt lgkmcnt(4)
	v_mfma_f32_32x32x16_bf16 v[50:65], v[158:161], v[66:69], v[50:65]
	v_add_u32_e32 v158, v145, v166
	v_add_u32_e32 v160, v144, v166
	ds_read_b64_tr_b16 v[158:159], v158
	ds_read_b64_tr_b16 v[160:161], v160
	v_mfma_f32_32x32x16_bf16 v[2:17], v[154:157], v[70:73], v[2:17]
	v_add_u32_e32 v154, v147, v168
	v_add_u32_e32 v156, v146, v168
	ds_read_b64_tr_b16 v[154:155], v154
	ds_read_b64_tr_b16 v[156:157], v156
	s_waitcnt lgkmcnt(6)
	v_mfma_f32_32x32x16_bf16 v[18:33], v[162:165], v[66:69], v[18:33]
	v_add_u32_e32 v162, v145, v168
	v_add_u32_e32 v164, v144, v168
	ds_read_b64_tr_b16 v[162:163], v162
	ds_read_b64_tr_b16 v[164:165], v164
	s_waitcnt lgkmcnt(6)
	v_mfma_f32_32x32x16_bf16 v[34:49], v[150:153], v[110:113], v[34:49]
	v_add_u32_e32 v150, v143, v166
	v_add_u32_e32 v152, v142, v166
	ds_read_b64_tr_b16 v[150:151], v150
	ds_read_b64_tr_b16 v[152:153], v152
	s_waitcnt lgkmcnt(6)
	v_mfma_f32_32x32x16_bf16 v[50:65], v[158:161], v[106:109], v[50:65]
	v_add_u32_e32 v158, v141, v166
	v_add_u32_e32 v160, v140, v166
	ds_read_b64_tr_b16 v[158:159], v158
	ds_read_b64_tr_b16 v[160:161], v160
	s_waitcnt lgkmcnt(6)
	v_mfma_f32_32x32x16_bf16 v[2:17], v[154:157], v[110:113], v[2:17]
	v_add_u32_e32 v154, v143, v168
	v_add_u32_e32 v156, v142, v168
	ds_read_b64_tr_b16 v[154:155], v154
	ds_read_b64_tr_b16 v[156:157], v156
	s_waitcnt lgkmcnt(6)
	v_mfma_f32_32x32x16_bf16 v[18:33], v[162:165], v[106:109], v[18:33]
	v_add_u32_e32 v162, v141, v168
	v_add_u32_e32 v164, v140, v168
	ds_read_b64_tr_b16 v[162:163], v162
	ds_read_b64_tr_b16 v[164:165], v164
	s_waitcnt lgkmcnt(6)
	v_mfma_f32_32x32x16_bf16 v[34:49], v[150:153], v[102:105], v[34:49]
	v_add_u32_e32 v150, v139, v166
	v_add_u32_e32 v152, v138, v166
	ds_read_b64_tr_b16 v[150:151], v150
	ds_read_b64_tr_b16 v[152:153], v152
	s_waitcnt lgkmcnt(6)
	v_mfma_f32_32x32x16_bf16 v[50:65], v[158:161], v[98:101], v[50:65]
	v_add_u32_e32 v158, v137, v166
	v_add_u32_e32 v160, v136, v166
	ds_read_b64_tr_b16 v[158:159], v158
	ds_read_b64_tr_b16 v[160:161], v160
	s_waitcnt lgkmcnt(6)
	v_mfma_f32_32x32x16_bf16 v[2:17], v[154:157], v[102:105], v[2:17]
	v_add_u32_e32 v154, v139, v168
	v_add_u32_e32 v156, v138, v168
	ds_read_b64_tr_b16 v[154:155], v154
	ds_read_b64_tr_b16 v[156:157], v156
	s_waitcnt lgkmcnt(6)
	v_mfma_f32_32x32x16_bf16 v[18:33], v[162:165], v[98:101], v[18:33]
	v_add_u32_e32 v162, v137, v168
	v_add_u32_e32 v164, v136, v168
	ds_read_b64_tr_b16 v[162:163], v162
	ds_read_b64_tr_b16 v[164:165], v164
	s_waitcnt lgkmcnt(6)
	v_mfma_f32_32x32x16_bf16 v[34:49], v[150:153], v[86:89], v[34:49]
	v_add_u32_e32 v150, v135, v166
	v_add_u32_e32 v152, v134, v166
	ds_read_b64_tr_b16 v[150:151], v150
	ds_read_b64_tr_b16 v[152:153], v152
	s_waitcnt lgkmcnt(6)
	v_mfma_f32_32x32x16_bf16 v[50:65], v[158:161], v[82:85], v[50:65]
	v_add_u32_e32 v158, v131, v166
	v_add_u32_e32 v160, v0, v166
	ds_read_b64_tr_b16 v[158:159], v158
	ds_read_b64_tr_b16 v[160:161], v160
	s_waitcnt lgkmcnt(6)
	v_mfma_f32_32x32x16_bf16 v[2:17], v[154:157], v[86:89], v[2:17]
	v_add_u32_e32 v154, v135, v168
	v_add_u32_e32 v156, v134, v168
	ds_read_b64_tr_b16 v[154:155], v154
	ds_read_b64_tr_b16 v[156:157], v156
	s_waitcnt lgkmcnt(6)
	v_mfma_f32_32x32x16_bf16 v[18:33], v[162:165], v[82:85], v[18:33]
	v_add_u32_e32 v162, v131, v168
	v_add_u32_e32 v164, v0, v168
	ds_read_b64_tr_b16 v[162:163], v162
	ds_read_b64_tr_b16 v[164:165], v164
	s_waitcnt lgkmcnt(6)
	v_mfma_f32_32x32x16_bf16 v[34:49], v[150:153], v[78:81], v[34:49]
	v_xor_b32_e32 v150, 0x180, v149
	v_xor_b32_e32 v149, 0x1c0, v149
	v_add_u32_e32 v151, v148, v150
	v_add_u32_e32 v148, v148, v149
	s_waitcnt lgkmcnt(4)
	v_mfma_f32_32x32x16_bf16 v[50:65], v[158:161], v[74:77], v[50:65]
	s_waitcnt lgkmcnt(2)
	v_mfma_f32_32x32x16_bf16 v[2:17], v[154:157], v[78:81], v[2:17]
	s_nop 9
	v_add_f32_e64 v36, v36, v52
	v_add_f32_e64 v37, v37, v53
	v_add_f32_e64 v34, v34, v50
	v_add_f32_e64 v35, v35, v51
	v_add_f32_e64 v40, v40, v56
	v_add_f32_e64 v41, v41, v57
	v_add_f32_e32 v38, v38, v54
	v_add_f32_e32 v39, v39, v55
	v_mul_f32_e32 v34, v130, v34
	v_mul_f32_e32 v35, v130, v35
	v_mul_f32_e32 v36, v130, v36
	v_mul_f32_e32 v37, v130, v37
	v_cvt_pk_bf16_f32 v34, v34, v35
	s_waitcnt lgkmcnt(0)
	v_mfma_f32_32x32x16_bf16 v[18:33], v[162:165], v[74:77], v[18:33]
	v_cvt_pk_bf16_f32 v35, v36, v37
	v_mul_f32_e64 v36, v130, v38
	v_mul_f32_e64 v37, v130, v39
	v_mul_f32_e64 v38, v130, v40
	v_mul_f32_e64 v39, v130, v41
	v_cvt_pk_bf16_f32 v36, v36, v37
	v_cvt_pk_bf16_f32 v37, v38, v39
	v_add_f32_e32 v44, v44, v60
	v_add_f32_e32 v45, v45, v61
	v_add_f32_e32 v42, v42, v58
	v_add_f32_e32 v43, v43, v59
	s_nop 2
	v_add_f32_e32 v4, v4, v20
	v_add_f32_e32 v5, v5, v21
	v_add_f32_e32 v2, v2, v18
	v_add_f32_e32 v3, v3, v19
	v_add_f32_e32 v8, v8, v24
	v_add_f32_e32 v9, v9, v25
	v_add_f32_e32 v6, v6, v22
	v_add_f32_e32 v7, v7, v23
	v_mul_f32_e32 v2, v130, v2
	v_mul_f32_e32 v3, v130, v3
	v_mul_f32_e32 v4, v130, v4
	v_mul_f32_e32 v5, v130, v5
	v_cvt_pk_bf16_f32 v2, v2, v3
	v_cvt_pk_bf16_f32 v3, v4, v5
	v_mul_f32_e32 v4, v130, v6
	v_mul_f32_e32 v5, v130, v7
	v_mul_f32_e32 v6, v130, v8
	v_mul_f32_e32 v7, v130, v9
	v_cvt_pk_bf16_f32 v4, v4, v5
	v_cvt_pk_bf16_f32 v5, v6, v7
	v_permlane32_swap_b32_e32 v34, v36
	v_permlane32_swap_b32_e32 v35, v37
	v_add_f32_e32 v12, v12, v28
	v_add_f32_e32 v13, v13, v29
	v_add_f32_e32 v10, v10, v26
	v_add_f32_e32 v11, v11, v27
	v_permlane32_swap_b32_e32 v2, v4
	v_permlane32_swap_b32_e32 v3, v5
	v_add_f32_e32 v48, v48, v64
	v_add_f32_e32 v49, v49, v65
	v_add_f32_e32 v46, v46, v62
	v_add_f32_e32 v47, v47, v63
	global_store_dwordx4 v[132:133], v[34:37], off offset:256
	v_add_f32_e32 v16, v16, v32
	v_add_f32_e32 v17, v17, v33
	v_add_f32_e32 v14, v14, v30
	v_add_f32_e32 v15, v15, v31
	v_mul_f32_e32 v34, v130, v42
	v_mul_f32_e32 v35, v130, v43
	v_mul_f32_e32 v36, v130, v44
	v_mul_f32_e32 v37, v130, v45
	global_store_dwordx4 v[132:133], v[2:5], off offset:320
	v_cvt_pk_bf16_f32 v34, v34, v35
	v_cvt_pk_bf16_f32 v35, v36, v37
	v_mul_f32_e32 v2, v130, v10
	v_mul_f32_e32 v3, v130, v11
	v_mul_f32_e32 v4, v130, v12
	v_mul_f32_e32 v5, v130, v13
	v_mul_f32_e32 v36, v130, v46
	v_mul_f32_e32 v37, v130, v47
	v_mul_f32_e32 v38, v130, v48
	v_mul_f32_e32 v39, v130, v49
	v_cvt_pk_bf16_f32 v2, v2, v3
	v_cvt_pk_bf16_f32 v3, v4, v5
	v_mul_f32_e32 v4, v130, v14
	v_mul_f32_e32 v5, v130, v15
	v_mul_f32_e32 v6, v130, v16
	v_mul_f32_e32 v7, v130, v17
	v_cvt_pk_bf16_f32 v36, v36, v37
	v_cvt_pk_bf16_f32 v37, v38, v39
	v_cvt_pk_bf16_f32 v4, v4, v5
	v_cvt_pk_bf16_f32 v5, v6, v7
	v_permlane32_swap_b32_e32 v34, v36
	v_permlane32_swap_b32_e32 v35, v37
	v_permlane32_swap_b32_e32 v2, v4
	v_permlane32_swap_b32_e32 v3, v5
	global_store_dwordx4 v[132:133], v[34:37], off offset:288
	global_store_dwordx4 v[132:133], v[2:5], off offset:352
	ds_read_b64_tr_b16 v[2:3], v151
	ds_read_b64_tr_b16 v[4:5], v151 offset:4096
	ds_read_b64_tr_b16 v[6:7], v148
	ds_read_b64_tr_b16 v[8:9], v148 offset:4096
	ds_read_b64_tr_b16 v[10:11], v151 offset:8192
	ds_read_b64_tr_b16 v[12:13], v151 offset:12288
	ds_read_b64_tr_b16 v[18:19], v148 offset:8192
	ds_read_b64_tr_b16 v[20:21], v148 offset:12288
	s_waitcnt lgkmcnt(6)
	v_mfma_f32_32x32x16_bf16 v[34:49], v[2:5], v[126:129], 0
	s_waitcnt lgkmcnt(2)
	v_mfma_f32_32x32x16_bf16 v[50:65], v[10:13], v[122:125], 0
	v_mfma_f32_32x32x16_bf16 v[2:17], v[6:9], v[126:129], 0
	s_waitcnt lgkmcnt(0)
	v_mfma_f32_32x32x16_bf16 v[18:33], v[18:21], v[122:125], 0
	ds_read_b64_tr_b16 v[126:127], v151 offset:16384
	ds_read_b64_tr_b16 v[128:129], v151 offset:20480
	ds_read_b64_tr_b16 v[152:153], v148 offset:16384
	ds_read_b64_tr_b16 v[154:155], v148 offset:20480
	ds_read_b64_tr_b16 v[156:157], v151 offset:24576
	ds_read_b64_tr_b16 v[158:159], v151 offset:28672
	ds_read_b64_tr_b16 v[122:123], v148 offset:24576
	ds_read_b64_tr_b16 v[124:125], v148 offset:28672
	s_waitcnt lgkmcnt(6)
	v_mfma_f32_32x32x16_bf16 v[34:49], v[126:129], v[118:121], v[34:49]
	s_waitcnt lgkmcnt(2)
	v_mfma_f32_32x32x16_bf16 v[50:65], v[156:159], v[114:117], v[50:65]
	v_mfma_f32_32x32x16_bf16 v[2:17], v[152:155], v[118:121], v[2:17]
	s_waitcnt lgkmcnt(0)
	v_mfma_f32_32x32x16_bf16 v[18:33], v[122:125], v[114:117], v[18:33]
	ds_read_b64_tr_b16 v[114:115], v151 offset:32768
	ds_read_b64_tr_b16 v[116:117], v151 offset:36864
	ds_read_b64_tr_b16 v[118:119], v148 offset:32768
	ds_read_b64_tr_b16 v[120:121], v148 offset:36864
	ds_read_b64_tr_b16 v[122:123], v151 offset:40960
	ds_read_b64_tr_b16 v[124:125], v151 offset:45056
	ds_read_b64_tr_b16 v[126:127], v148 offset:40960
	ds_read_b64_tr_b16 v[128:129], v148 offset:45056
	s_waitcnt lgkmcnt(6)
	v_mfma_f32_32x32x16_bf16 v[34:49], v[114:117], v[94:97], v[34:49]
	s_waitcnt lgkmcnt(2)
	v_mfma_f32_32x32x16_bf16 v[50:65], v[122:125], v[90:93], v[50:65]
	v_mfma_f32_32x32x16_bf16 v[2:17], v[118:121], v[94:97], v[2:17]
	s_waitcnt lgkmcnt(0)
	v_mfma_f32_32x32x16_bf16 v[18:33], v[126:129], v[90:93], v[18:33]
	ds_read_b64_tr_b16 v[90:91], v151 offset:49152
	ds_read_b64_tr_b16 v[92:93], v151 offset:53248
	ds_read_b64_tr_b16 v[94:95], v148 offset:49152
	ds_read_b64_tr_b16 v[96:97], v148 offset:53248
	ds_read_b64_tr_b16 v[114:115], v151 offset:57344
	ds_read_b64_tr_b16 v[116:117], v151 offset:61440
	ds_read_b64_tr_b16 v[118:119], v148 offset:57344
	ds_read_b64_tr_b16 v[120:121], v148 offset:61440
	s_waitcnt lgkmcnt(6)
	v_mfma_f32_32x32x16_bf16 v[34:49], v[90:93], v[70:73], v[34:49]
	v_add_u32_e32 v90, v145, v150
	v_add_u32_e32 v92, v144, v150
	ds_read_b64_tr_b16 v[90:91], v90
	ds_read_b64_tr_b16 v[92:93], v92
	s_waitcnt lgkmcnt(4)
	v_mfma_f32_32x32x16_bf16 v[50:65], v[114:117], v[66:69], v[50:65]
	v_mfma_f32_32x32x16_bf16 v[2:17], v[94:97], v[70:73], v[2:17]
	v_add_u32_e32 v70, v147, v149
	v_add_u32_e32 v72, v146, v149
	v_add_u32_e32 v94, v145, v149
	v_add_u32_e32 v96, v144, v149
	ds_read_b64_tr_b16 v[70:71], v70
	ds_read_b64_tr_b16 v[72:73], v72
	ds_read_b64_tr_b16 v[94:95], v94
	ds_read_b64_tr_b16 v[96:97], v96
	s_waitcnt lgkmcnt(6)
	v_mfma_f32_32x32x16_bf16 v[18:33], v[118:121], v[66:69], v[18:33]
	v_add_u32_e32 v66, v147, v150
	v_add_u32_e32 v68, v146, v150
	ds_read_b64_tr_b16 v[66:67], v66
	ds_read_b64_tr_b16 v[68:69], v68
	s_waitcnt lgkmcnt(0)
	v_mfma_f32_32x32x16_bf16 v[34:49], v[66:69], v[110:113], v[34:49]
	v_add_u32_e32 v66, v143, v150
	v_add_u32_e32 v68, v142, v150
	ds_read_b64_tr_b16 v[66:67], v66
	ds_read_b64_tr_b16 v[68:69], v68
	v_mfma_f32_32x32x16_bf16 v[50:65], v[90:93], v[106:109], v[50:65]
	v_add_u32_e32 v90, v141, v150
	v_add_u32_e32 v92, v140, v150
	ds_read_b64_tr_b16 v[90:91], v90
	ds_read_b64_tr_b16 v[92:93], v92
	v_mfma_f32_32x32x16_bf16 v[2:17], v[70:73], v[110:113], v[2:17]
	v_add_u32_e32 v70, v143, v149
	v_add_u32_e32 v72, v142, v149
	ds_read_b64_tr_b16 v[70:71], v70
	ds_read_b64_tr_b16 v[72:73], v72
	v_mfma_f32_32x32x16_bf16 v[18:33], v[94:97], v[106:109], v[18:33]
	v_add_u32_e32 v94, v141, v149
	v_add_u32_e32 v96, v140, v149
	ds_read_b64_tr_b16 v[94:95], v94
	ds_read_b64_tr_b16 v[96:97], v96
	s_waitcnt lgkmcnt(6)
	v_mfma_f32_32x32x16_bf16 v[34:49], v[66:69], v[102:105], v[34:49]
	v_add_u32_e32 v66, v139, v150
	v_add_u32_e32 v68, v138, v150
	ds_read_b64_tr_b16 v[66:67], v66
	ds_read_b64_tr_b16 v[68:69], v68
	s_waitcnt lgkmcnt(6)
	v_mfma_f32_32x32x16_bf16 v[50:65], v[90:93], v[98:101], v[50:65]
	v_add_u32_e32 v90, v137, v150
	v_add_u32_e32 v92, v136, v150
	ds_read_b64_tr_b16 v[90:91], v90
	ds_read_b64_tr_b16 v[92:93], v92
	s_waitcnt lgkmcnt(6)
	v_mfma_f32_32x32x16_bf16 v[2:17], v[70:73], v[102:105], v[2:17]
	v_add_u32_e32 v70, v139, v149
	v_add_u32_e32 v72, v138, v149
	ds_read_b64_tr_b16 v[70:71], v70
	ds_read_b64_tr_b16 v[72:73], v72
	s_waitcnt lgkmcnt(6)
	v_mfma_f32_32x32x16_bf16 v[18:33], v[94:97], v[98:101], v[18:33]
	v_add_u32_e32 v94, v137, v149
	v_add_u32_e32 v96, v136, v149
	ds_read_b64_tr_b16 v[94:95], v94
	ds_read_b64_tr_b16 v[96:97], v96
	s_waitcnt lgkmcnt(6)
	v_mfma_f32_32x32x16_bf16 v[34:49], v[66:69], v[86:89], v[34:49]
	v_add_u32_e32 v66, v135, v150
	v_add_u32_e32 v68, v134, v150
	ds_read_b64_tr_b16 v[66:67], v66
	ds_read_b64_tr_b16 v[68:69], v68
	s_waitcnt lgkmcnt(6)
	v_mfma_f32_32x32x16_bf16 v[50:65], v[90:93], v[82:85], v[50:65]
	s_waitcnt lgkmcnt(4)
	v_mfma_f32_32x32x16_bf16 v[2:17], v[70:73], v[86:89], v[2:17]
	v_add_u32_e32 v70, v135, v149
	v_add_u32_e32 v72, v134, v149
	v_add_u32_e32 v86, v131, v149
	ds_read_b64_tr_b16 v[70:71], v70
	ds_read_b64_tr_b16 v[72:73], v72
	ds_read_b64_tr_b16 v[86:87], v86
	s_waitcnt lgkmcnt(5)
	v_mfma_f32_32x32x16_bf16 v[18:33], v[94:97], v[82:85], v[18:33]
	v_add_u32_e32 v82, v131, v150
	v_add_u32_e32 v84, v0, v150
	v_add_u32_e32 v0, v0, v149
	ds_read_b64_tr_b16 v[82:83], v82
	ds_read_b64_tr_b16 v[84:85], v84
	ds_read_b64_tr_b16 v[88:89], v0
	s_waitcnt lgkmcnt(6)
	v_mfma_f32_32x32x16_bf16 v[34:49], v[66:69], v[78:81], v[34:49]
	s_waitcnt lgkmcnt(1)
	v_mfma_f32_32x32x16_bf16 v[50:65], v[82:85], v[74:77], v[50:65]
	v_mfma_f32_32x32x16_bf16 v[2:17], v[70:73], v[78:81], v[2:17]
	s_nop 10
	v_add_f32_e64 v36, v36, v52
	v_add_f32_e64 v37, v37, v53
	v_add_f32_e64 v34, v34, v50
	v_add_f32_e64 v35, v35, v51
	v_add_f32_e64 v40, v40, v56
	v_add_f32_e64 v41, v41, v57
	v_add_f32_e32 v38, v38, v54
	v_add_f32_e32 v39, v39, v55
	v_mul_f32_e32 v34, v130, v34
	v_mul_f32_e32 v35, v130, v35
	v_mul_f32_e32 v36, v130, v36
	v_mul_f32_e32 v37, v130, v37
	v_cvt_pk_bf16_f32 v34, v34, v35
	s_waitcnt lgkmcnt(0)
	v_mfma_f32_32x32x16_bf16 v[18:33], v[86:89], v[74:77], v[18:33]
	v_cvt_pk_bf16_f32 v35, v36, v37
	v_mul_f32_e64 v36, v130, v38
	v_mul_f32_e64 v37, v130, v39
	v_mul_f32_e64 v38, v130, v40
	v_mul_f32_e64 v39, v130, v41
	v_cvt_pk_bf16_f32 v36, v36, v37
	v_cvt_pk_bf16_f32 v37, v38, v39
	v_add_f32_e32 v44, v44, v60
	v_add_f32_e32 v45, v45, v61
	v_add_f32_e32 v42, v42, v58
	v_add_f32_e32 v43, v43, v59
	s_nop 2
	v_add_f32_e32 v4, v4, v20
	v_add_f32_e32 v5, v5, v21
	v_add_f32_e32 v2, v2, v18
	v_add_f32_e32 v3, v3, v19
	v_add_f32_e32 v8, v8, v24
	v_add_f32_e32 v9, v9, v25
	v_add_f32_e32 v6, v6, v22
	v_add_f32_e32 v7, v7, v23
	v_mul_f32_e32 v2, v130, v2
	v_mul_f32_e32 v3, v130, v3
	v_mul_f32_e32 v4, v130, v4
	v_mul_f32_e32 v5, v130, v5
	v_cvt_pk_bf16_f32 v2, v2, v3
	v_cvt_pk_bf16_f32 v3, v4, v5
	v_mul_f32_e32 v4, v130, v6
	v_mul_f32_e32 v5, v130, v7
	v_mul_f32_e32 v6, v130, v8
	v_mul_f32_e32 v7, v130, v9
	v_cvt_pk_bf16_f32 v4, v4, v5
	v_cvt_pk_bf16_f32 v5, v6, v7
	v_permlane32_swap_b32_e32 v34, v36
	v_permlane32_swap_b32_e32 v35, v37
	v_add_f32_e32 v12, v12, v28
	v_add_f32_e32 v13, v13, v29
	v_add_f32_e32 v10, v10, v26
	v_add_f32_e32 v11, v11, v27
	v_permlane32_swap_b32_e32 v2, v4
	v_permlane32_swap_b32_e32 v3, v5
	v_add_f32_e32 v48, v48, v64
	v_add_f32_e32 v49, v49, v65
	v_add_f32_e32 v46, v46, v62
	v_add_f32_e32 v47, v47, v63
	global_store_dwordx4 v[132:133], v[34:37], off offset:384
	v_add_f32_e32 v16, v16, v32
	v_add_f32_e32 v17, v17, v33
	v_add_f32_e32 v14, v14, v30
	v_add_f32_e32 v15, v15, v31
	v_mul_f32_e32 v34, v130, v42
	v_mul_f32_e32 v35, v130, v43
	v_mul_f32_e32 v36, v130, v44
	v_mul_f32_e32 v37, v130, v45
	global_store_dwordx4 v[132:133], v[2:5], off offset:448
	v_cvt_pk_bf16_f32 v34, v34, v35
	v_cvt_pk_bf16_f32 v35, v36, v37
	v_mul_f32_e32 v2, v130, v10
	v_mul_f32_e32 v3, v130, v11
	v_mul_f32_e32 v4, v130, v12
	v_mul_f32_e32 v5, v130, v13
	v_mul_f32_e32 v36, v130, v46
	v_mul_f32_e32 v37, v130, v47
	v_mul_f32_e32 v38, v130, v48
	v_mul_f32_e32 v39, v130, v49
	v_cvt_pk_bf16_f32 v2, v2, v3
	v_cvt_pk_bf16_f32 v3, v4, v5
	v_mul_f32_e32 v4, v130, v14
	v_mul_f32_e32 v5, v130, v15
	v_mul_f32_e32 v6, v130, v16
	v_mul_f32_e32 v7, v130, v17
	v_cvt_pk_bf16_f32 v36, v36, v37
	v_cvt_pk_bf16_f32 v37, v38, v39
	v_cvt_pk_bf16_f32 v4, v4, v5
	v_cvt_pk_bf16_f32 v5, v6, v7
	v_permlane32_swap_b32_e32 v34, v36
	v_permlane32_swap_b32_e32 v35, v37
	v_permlane32_swap_b32_e32 v2, v4
	v_permlane32_swap_b32_e32 v3, v5
	global_store_dwordx4 v[132:133], v[34:37], off offset:416
	global_store_dwordx4 v[132:133], v[2:5], off offset:480
	s_branch .LBB0_699
